# static s_setprio 1 for waves 4-7 for the whole of both attention passes (restored to 0 at pass end)
# baseline (speedup 1.0000x reference)
; __device__ __forceinline__ float bf2f(unsigned short b) { return __uint_as_float((unsigned)b << 16); }
; __device__ __forceinline__ float sum_x32(float v) { auto rr = __builtin_amdgcn_permlane32_swap(__float_as_uint(v), __float_as_uint(v), false, false); return __uint_as_float(rr[0]) + __uint_as_float(rr[1]); }
; template <int DV>
; __device__ __forceinline__ void attn_pass(const int tid, unsigned char* smem, const bf16_t* Q0, int qpitch, const bf16_t* Kb, int kpitch, const bf16_t* Vb, int vpitch,
;                                           int b, int ntiles, float kmax, f32x16 (&o)[DV / 32], float& linv) {
;     constexpr int KP = 144, VP = DV * 2 + 64, KBYTES = 64 * KP, VBYTES = 64 * VP, BUF = KBYTES + VBYTES, NV = DV / 64;
;     const int lane = tid & 63, wid = __builtin_amdgcn_readfirstlane(tid >> 6), r32 = lane & 31, hi = lane >> 5;
;     bf16x8 qf[4];
;     { const bf16_t* qp = Q0 + (size_t)(wid * 32 + r32) * qpitch + 8 * hi;
; #pragma unroll
;       for (int ds = 0; ds < 4; ++ds) qf[ds] = *(const bf16x8*)(qp + 16 * ds); }
;     float ssq = 0.f;
; #pragma unroll
;     for (int ds = 0; ds < 4; ++ds)
; #pragma unroll
;         for (int j = 0; j < 8; ++j) { const float f = bf2f((unsigned short)qf[ds][j]); ssq += f * f; }
;     ssq = sum_x32(ssq);
;     const float nshift = -sqrtf(ssq) * kmax;
.LBB0_405:
	s_xor_b64 s[14:15], s[16:17], -1
	s_lshl_b64 s[0:1], s[0:1], 1
	s_add_u32 s2, s28, s0
	s_addc_u32 s3, s29, s1
	s_add_u32 s16, s30, s0
	v_readfirstlane_b32 s0, v197
	s_addc_u32 s17, s31, s1
	s_ashr_i32 s0, s0, 1
	s_andn2_b32 s0, s0, 31
	v_or_b32_e32 v0, s0, v218
	v_ashrrev_i32_e32 v1, 31, v0
	v_lshlrev_b64 v[0:1], 11, v[0:1]
	v_lshl_add_u64 v[0:1], s[2:3], 0, v[0:1]
	v_lshl_add_u64 v[0:1], v[0:1], 0, v[192:193]
	global_load_dwordx4 v[96:99], v[0:1], off
	global_load_dwordx4 v[100:103], v[0:1], off offset:32
	global_load_dwordx4 v[104:107], v[0:1], off offset:64
	global_load_dwordx4 v[108:111], v[0:1], off offset:96
	s_mov_b32 s0, 0xf800000
	v_mov_b32_e32 v169, v193
	v_readlane_b32 s68, v251, 29
	v_readlane_b32 s69, v251, 30
	s_lshl_b32 s2, s26, 8
	s_add_u32 s68, s68, s2
	s_addc_u32 s69, s69, 0
	s_mov_b64 s[66:67], s[16:17]
	s_lshl_b32 s2, s10, 8
	s_add_i32 s65, s2, 0x8000
	s_lshl_b32 s2, s10, 13
	s_add_i32 s32, s2, 0xffffff00
	s_lshr_b32 s56, s27, 6
	s_lshl_b32 s56, s56, 10
	v_bfe_u32 v234, v136, 1, 3
	v_and_b32_e32 v235, 7, v197
	v_xor_b32_e32 v234, v234, v235
	v_lshlrev_b32_e32 v234, 4, v234
	v_lshl_add_u32 v166, v136, 10, v234
	v_and_b32_e32 v236, 3, v134
	v_lshlrev_b32_e32 v236, 2, v236
	v_and_b32_e32 v237, 15, v197
	v_xor_b32_e32 v236, v236, v237
	v_lshlrev_b32_e32 v236, 4, v236
	v_lshl_add_u32 v167, v134, 10, v236
	v_add_u32_e32 v132, 0x8000, v167
	s_mov_b32 s70, 0
	s_cmp_lt_u32 s70, 4
	s_cselect_b32 s2, s65, s32
	s_lshl_b32 s3, s70, 6
	s_add_i32 s2, s2, s3
	s_lshl_b32 s2, s2, 10
	s_add_u32 s60, s66, s2
	s_addc_u32 s61, s67, 0
	s_cmp_lt_u32 s70, 4
	s_cselect_b32 s2, s65, s32
	s_lshl_b32 s3, s70, 6
	s_add_i32 s2, s2, s3
	s_lshl_b32 s2, s2, 10
	s_add_u32 s62, s68, s2
	s_addc_u32 s63, s69, 0
	s_mov_b32 m0, s56
	s_nop 0
	global_load_lds_dwordx4 v166, s[60:61]
	s_mov_b32 s70, 1
	s_cmp_lt_u32 s70, 4
	s_cselect_b32 s2, s65, s32
	s_lshl_b32 s3, s70, 6
	s_add_i32 s2, s2, s3
	s_lshl_b32 s2, s2, 10
	s_add_u32 s60, s66, s2
	s_addc_u32 s61, s67, 0
	s_add_i32 m0, s56, 0x6000
	s_nop 0
	global_load_lds_dwordx4 v166, s[60:61]
	s_add_i32 m0, s56, 0x8000
	s_nop 0
	global_load_lds_dwordx4 v167, s[62:63]
	s_add_i32 m0, s56, 0xa000
	s_nop 0
	global_load_lds_dwordx4 v132, s[62:63]
	s_cmp_lt_u32 s70, 4
	s_cselect_b32 s2, s65, s32
	s_lshl_b32 s3, s70, 6
	s_add_i32 s2, s2, s3
	s_lshl_b32 s2, s2, 10
	s_add_u32 s62, s68, s2
	s_addc_u32 s63, s69, 0
	s_mov_b32 s70, 2
	s_cmp_lt_u32 s70, 4
	s_cselect_b32 s2, s65, s32
	s_lshl_b32 s3, s70, 6
	s_add_i32 s2, s2, s3
	s_lshl_b32 s2, s2, 10
	s_add_u32 s60, s66, s2
	s_addc_u32 s61, s67, 0
	s_add_i32 m0, s56, 0xc000
	s_nop 0
	global_load_lds_dwordx4 v166, s[60:61]
	s_add_i32 m0, s56, 0xe000
	s_nop 0
	global_load_lds_dwordx4 v167, s[62:63]
	s_add_i32 m0, s56, 0x10000
	s_nop 0
	global_load_lds_dwordx4 v132, s[62:63]
	v_mov_b32_e32 v63, v193
	s_waitcnt vmcnt(10)
	v_and_b32_e32 v1, 0xffff0000, v96
	v_lshlrev_b32_e32 v0, 16, v96
	v_mul_f32_e32 v2, v1, v1
	v_fmac_f32_e32 v2, v0, v0
	v_lshlrev_b32_e32 v0, 16, v97
	v_fmac_f32_e32 v2, v0, v0
	v_and_b32_e32 v0, 0xffff0000, v97
	v_fmac_f32_e32 v2, v0, v0
	v_lshlrev_b32_e32 v0, 16, v98
	v_fmac_f32_e32 v2, v0, v0
	v_and_b32_e32 v0, 0xffff0000, v98
	v_fmac_f32_e32 v2, v0, v0
	v_lshlrev_b32_e32 v0, 16, v99
	v_fmac_f32_e32 v2, v0, v0
	v_and_b32_e32 v0, 0xffff0000, v99
	v_fmac_f32_e32 v2, v0, v0
	s_waitcnt vmcnt(9)
	v_lshlrev_b32_e32 v0, 16, v100
	v_fmac_f32_e32 v2, v0, v0
	v_and_b32_e32 v0, 0xffff0000, v100
	v_fmac_f32_e32 v2, v0, v0
	v_lshlrev_b32_e32 v0, 16, v101
	v_fmac_f32_e32 v2, v0, v0
	v_and_b32_e32 v0, 0xffff0000, v101
	v_fmac_f32_e32 v2, v0, v0
	v_lshlrev_b32_e32 v0, 16, v102
	v_fmac_f32_e32 v2, v0, v0
	v_and_b32_e32 v0, 0xffff0000, v102
	v_fmac_f32_e32 v2, v0, v0
	v_lshlrev_b32_e32 v0, 16, v103
	v_fmac_f32_e32 v2, v0, v0
	v_and_b32_e32 v0, 0xffff0000, v103
	v_fmac_f32_e32 v2, v0, v0
	s_waitcnt vmcnt(8)
	v_lshlrev_b32_e32 v0, 16, v104
	v_fmac_f32_e32 v2, v0, v0
	v_and_b32_e32 v0, 0xffff0000, v104
	v_fmac_f32_e32 v2, v0, v0
	v_lshlrev_b32_e32 v0, 16, v105
	v_fmac_f32_e32 v2, v0, v0
	v_and_b32_e32 v0, 0xffff0000, v105
	v_fmac_f32_e32 v2, v0, v0
	v_lshlrev_b32_e32 v0, 16, v106
	v_fmac_f32_e32 v2, v0, v0
	v_and_b32_e32 v0, 0xffff0000, v106
	v_fmac_f32_e32 v2, v0, v0
	v_lshlrev_b32_e32 v0, 16, v107
	v_fmac_f32_e32 v2, v0, v0
	v_and_b32_e32 v0, 0xffff0000, v107
	v_fmac_f32_e32 v2, v0, v0
	s_waitcnt vmcnt(7)
	v_lshlrev_b32_e32 v0, 16, v108
	v_fmac_f32_e32 v2, v0, v0
	v_and_b32_e32 v0, 0xffff0000, v108
	v_fmac_f32_e32 v2, v0, v0
	v_lshlrev_b32_e32 v0, 16, v109
	v_fmac_f32_e32 v2, v0, v0
	v_and_b32_e32 v0, 0xffff0000, v109
	v_fmac_f32_e32 v2, v0, v0
	v_and_b32_e32 v1, 0xffff0000, v110
	v_lshlrev_b32_e32 v0, 16, v110
	v_pk_mul_f32 v[0:1], v[0:1], v[0:1]
	s_nop 0
	v_add_f32_e32 v0, v0, v2
	v_add_f32_e32 v2, v1, v0
	v_and_b32_e32 v1, 0xffff0000, v111
	v_lshlrev_b32_e32 v0, 16, v111
	v_pk_mul_f32 v[0:1], v[0:1], v[0:1]
	s_nop 0
	v_add_f32_e32 v0, v0, v2
	v_add_f32_e32 v0, v1, v0
	v_mov_b32_e32 v1, v0
	s_nop 1
	v_permlane32_swap_b32_e32 v0, v1
	v_add_f32_e32 v0, v0, v1
	v_cmp_gt_f32_e32 vcc, s0, v0
	v_mul_f32_e32 v1, 0x4f800000, v0
	s_nop 0
	v_cndmask_b32_e32 v0, v0, v1, vcc
	v_sqrt_f32_e32 v1, v0
	s_nop 0
	v_add_u32_e32 v2, -1, v1
	v_fma_f32 v3, -v2, v1, v0
	v_cmp_ge_f32_e64 s[0:1], 0, v3
	v_add_u32_e32 v3, 1, v1
	s_nop 0
	v_cndmask_b32_e64 v2, v1, v2, s[0:1]
	v_fma_f32 v1, -v3, v1, v0
	v_cmp_lt_f32_e64 s[0:1], 0, v1
	s_nop 1
	v_cndmask_b32_e64 v1, v2, v3, s[0:1]
	v_mul_f32_e32 v2, 0x37800000, v1
	v_cndmask_b32_e32 v1, v1, v2, vcc
	v_cmp_class_f32_e32 vcc, v0, v227
	s_nop 1
	v_cndmask_b32_e32 v0, v1, v0, vcc
	v_mul_f32_e64 v32, v214, -v0
	s_cmp_ge_u32 s27, 0x100
	s_cbranch_scc0 .Lc_prio_skip
	s_setprio 1
; template <int DV>
; __device__ __forceinline__ void attn_pass(const int tid, unsigned char* smem, const bf16_t* Q0, int qpitch, const bf16_t* Kb, int kpitch, const bf16_t* Vb, int vpitch,
;                                           int b, int ntiles, float kmax, f32x16 (&o)[DV / 32], float& linv) {
;     ...
; #pragma unroll
;     for (int d0 = 0; d0 < DV / 32; ++d0)
; #pragma unroll
;         for (int r = 0; r < 16; ++r) o[d0][r] = 0.f;
;     float lsum = 0.f;
;     const int krow = tid >> 3, kch = tid & 7;
;     u32x4 kreg, vreg[NV];
;     auto tile_row = [&](int kt) -> size_t { return kt < 4 ? (size_t)(NLAT + 256 * b + 64 * kt) : (size_t)(SEQ * b + 64 * (kt - 4)); };
;     auto gload = [&](int kt) {
;         const size_t rb = tile_row(kt);
;         kreg = *(const u32x4*)(Kb + (rb + krow) * kpitch + 8 * kch);
; #pragma unroll
;         for (int i = 0; i < NV; ++i) { const int item = tid + 512 * i; const int vr = (DV == 64) ? (item >> 3) : (item >> 4), vc = (DV == 64) ? (item & 7) : (item & 15);
;             vreg[i] = *(const u32x4*)(Vb + (rb + vr) * vpitch + 8 * vc); }
;     };
;     auto lwrite = [&](int buf) {
;         unsigned char* Ks = smem + buf * BUF; unsigned char* Vs = Ks + KBYTES;
;         *(u32x4*)(Ks + krow * KP + 16 * kch) = kreg;
; #pragma unroll
;         for (int i = 0; i < NV; ++i) { const int item = tid + 512 * i; const int vr = (DV == 64) ? (item >> 3) : (item >> 4), vc = (DV == 64) ? (item & 7) : (item & 15);
;             *(u32x4*)(Vs + vr * VP + 16 * vc) = vreg[i]; }
;     };
;     gload(0); lwrite(0); __syncthreads();
;     const int nhalf = (lane >> 4) & 1, q4 = (lane & 15) >> 2, p4 = lane & 3;
;     for (int kt = 0; kt < ntiles; ++kt) {
;         if (kt + 1 < ntiles) gload(kt + 1);
;         const unsigned char* Ks = smem + (kt & 1) * BUF; const unsigned char* Vs = Ks + KBYTES;
;         const unsigned char* kp = Ks + r32 * KP + hi * 16;
;         bf16x8 pf[2][2];
; #pragma unroll
;         for (int kb = 0; kb < 2; ++kb) {
;             f32x16 s;
; #pragma unroll
;             for (int r = 0; r < 16; ++r) s[r] = nshift;
; #pragma unroll
;             for (int ds = 0; ds < 4; ++ds) {
;                 const bf16x8 kf = *(const bf16x8*)(kp + kb * 32 * KP + ds * 32);
;                 s = __builtin_amdgcn_mfma_f32_32x32x16_bf16(kf, qf[ds], s, 0, 0, 0);
;             }
;             float ls = 0.f;
; #pragma unroll
.Lc_prio_skip:
	v_mov_b32_e32 v33, v32
	v_mov_b32_e32 v34, v32
	v_mov_b32_e32 v35, v32
	v_mov_b32_e32 v36, v32
	v_mov_b32_e32 v37, v32
	v_mov_b32_e32 v38, v32
	v_mov_b32_e32 v39, v32
	v_mov_b32_e32 v40, v32
	v_mov_b32_e32 v41, v32
	v_mov_b32_e32 v42, v32
	v_mov_b32_e32 v43, v32
	v_mov_b32_e32 v44, v32
	v_mov_b32_e32 v45, v32
	v_mov_b32_e32 v46, v32
	v_mov_b32_e32 v47, v32
	v_mov_b32_e32 v0, 0
	v_mov_b32_e32 v1, 0
	v_mov_b32_e32 v2, 0
	v_mov_b32_e32 v3, 0
	v_mov_b32_e32 v4, 0
	v_mov_b32_e32 v5, 0
	v_mov_b32_e32 v6, 0
	v_mov_b32_e32 v7, 0
	v_mov_b32_e32 v8, 0
	v_mov_b32_e32 v9, 0
	v_mov_b32_e32 v10, 0
	v_mov_b32_e32 v11, 0
	v_mov_b32_e32 v12, 0
	v_mov_b32_e32 v13, 0
	v_mov_b32_e32 v14, 0
	v_mov_b32_e32 v15, 0
	v_mov_b32_e32 v16, 0
	v_mov_b32_e32 v17, 0
	v_mov_b32_e32 v18, 0
	v_mov_b32_e32 v19, 0
	v_mov_b32_e32 v20, 0
	v_mov_b32_e32 v21, 0
	v_mov_b32_e32 v22, 0
	v_mov_b32_e32 v23, 0
	v_mov_b32_e32 v24, 0
	v_mov_b32_e32 v25, 0
	v_mov_b32_e32 v26, 0
	v_mov_b32_e32 v27, 0
	v_mov_b32_e32 v28, 0
	v_mov_b32_e32 v29, 0
	v_mov_b32_e32 v30, 0
	v_mov_b32_e32 v31, 0
	v_mov_b32_e32 v48, 0
	v_mov_b32_e32 v49, 0
	v_mov_b32_e32 v50, 0
	v_mov_b32_e32 v51, 0
	v_mov_b32_e32 v52, 0
	v_mov_b32_e32 v53, 0
	v_mov_b32_e32 v54, 0
	v_mov_b32_e32 v55, 0
	v_mov_b32_e32 v56, 0
	v_mov_b32_e32 v57, 0
	v_mov_b32_e32 v58, 0
	v_mov_b32_e32 v59, 0
	v_mov_b32_e32 v60, 0
	v_mov_b32_e32 v61, 0
	v_mov_b32_e32 v62, 0
	v_mov_b32_e32 v63, 0
	v_mov_b32_e32 v64, 0
	v_mov_b32_e32 v65, 0
	v_mov_b32_e32 v66, 0
	v_mov_b32_e32 v67, 0
	v_mov_b32_e32 v68, 0
	v_mov_b32_e32 v69, 0
	v_mov_b32_e32 v70, 0
	v_mov_b32_e32 v71, 0
	v_mov_b32_e32 v72, 0
	v_mov_b32_e32 v73, 0
	v_mov_b32_e32 v74, 0
	v_mov_b32_e32 v75, 0
	v_mov_b32_e32 v76, 0
	v_mov_b32_e32 v77, 0
	v_mov_b32_e32 v78, 0
	v_mov_b32_e32 v79, 0
	v_mov_b32_e32 v169, 0
	v_bfe_u32 v234, v218, 1, 3
	v_lshrrev_b32_e32 v235, 4, v138
	v_xor_b32_e32 v234, v234, v235
	v_xor_b32_e32 v235, 0, v234
	v_lshlrev_b32_e32 v235, 4, v235
	v_lshl_or_b32 v174, v218, 7, v235
	v_add_u32_e32 v128, 0xc000, v174
	v_xor_b32_e32 v235, 2, v234
	v_lshlrev_b32_e32 v235, 4, v235
	v_lshl_or_b32 v175, v218, 7, v235
	v_add_u32_e32 v129, 0xc000, v175
	v_xor_b32_e32 v235, 4, v234
	v_lshlrev_b32_e32 v235, 4, v235
	v_lshl_or_b32 v210, v218, 7, v235
	v_add_u32_e32 v130, 0xc000, v210
	v_xor_b32_e32 v235, 6, v234
	v_lshlrev_b32_e32 v235, 4, v235
	v_lshl_or_b32 v211, v218, 7, v235
	v_add_u32_e32 v131, 0xc000, v211
	v_and_b32_e32 v236, 3, v215
	v_xor_b32_e32 v237, 0, v236
	v_lshl_add_u32 v237, v237, 6, v221
	v_lshl_add_u32 v142, v215, 8, v237
	v_add_u32_e32 v170, 0xc000, v142
	v_xor_b32_e32 v237, 1, v236
	v_lshl_add_u32 v237, v237, 6, v221
	v_lshl_add_u32 v143, v215, 8, v237
	v_add_u32_e32 v171, 0xc000, v143
	v_xor_b32_e32 v237, 2, v236
	v_lshl_add_u32 v237, v237, 6, v221
	v_lshl_add_u32 v146, v215, 8, v237
	v_add_u32_e32 v172, 0xc000, v146
	v_xor_b32_e32 v237, 3, v236
	v_lshl_add_u32 v237, v237, 6, v221
	v_lshl_add_u32 v147, v215, 8, v237
	v_add_u32_e32 v173, 0xc000, v147
	s_mov_b32 s59, 0
	s_waitcnt vmcnt(3)
	s_barrier
	ds_read_b128 v[198:201], v174
	ds_read_b128 v[202:205], v175
	ds_read_b128 v[206:209], v210
	ds_read_b128 v[150:153], v211
	s_waitcnt lgkmcnt(3)
	v_mfma_f32_32x32x16_bf16 v[80:95], v[198:201], v[96:99], v[32:47]
	ds_read_b128 v[198:201], v174 offset:4096
	s_add_i32 s71, s25, -1
	s_add_i32 s70, s59, 3
	s_min_u32 s70, s70, s71
	s_cmp_lt_u32 s70, 4
	s_cselect_b32 s2, s65, s32
	s_lshl_b32 s3, s70, 6
	s_add_i32 s2, s2, s3
	s_lshl_b32 s2, s2, 10
	s_add_u32 s60, s66, s2
	s_addc_u32 s61, s67, 0
	s_add_i32 s70, s59, 2
	s_min_u32 s70, s70, s71
	s_cmp_lt_u32 s70, 4
	s_cselect_b32 s2, s65, s32
	s_lshl_b32 s3, s70, 6
	s_add_i32 s2, s2, s3
	s_lshl_b32 s2, s2, 10
	s_add_u32 s62, s68, s2
	s_addc_u32 s63, s69, 0
	s_waitcnt lgkmcnt(3)
	v_mfma_f32_32x32x16_bf16 v[80:95], v[202:205], v[100:103], v[80:95]
	ds_read_b128 v[202:205], v175 offset:4096
	s_add_i32 m0, s56, 0x12000
	s_nop 0
	global_load_lds_dwordx4 v166, s[60:61]
	s_waitcnt lgkmcnt(3)
	v_mfma_f32_32x32x16_bf16 v[80:95], v[206:209], v[104:107], v[80:95]
	ds_read_b128 v[206:209], v210 offset:4096
	s_add_i32 m0, s56, 0x14000
	s_nop 0
	global_load_lds_dwordx4 v167, s[62:63]
	s_add_i32 m0, s56, 0x16000
	s_nop 0
	global_load_lds_dwordx4 v132, s[62:63]
	s_waitcnt lgkmcnt(3)
	v_mfma_f32_32x32x16_bf16 v[80:95], v[150:153], v[108:111], v[80:95]
	ds_read_b128 v[150:153], v211 offset:4096
	s_nop 7
	s_waitcnt lgkmcnt(3)
	v_mfma_f32_32x32x16_bf16 v[112:127], v[198:201], v[96:99], v[32:47]
	ds_read_b128 v[198:201], v174 offset:24576
	ds_read_b64_tr_b16 v[154:155], v142 offset:32768
	ds_read_b64_tr_b16 v[156:157], v142 offset:34816
	v_exp_f32_e32 v80, v80
	v_exp_f32_e32 v81, v81
	v_exp_f32_e32 v82, v82
	v_add_f32_e32 v169, v169, v80
	v_exp_f32_e32 v83, v83
	v_add_f32_e32 v169, v169, v81
	v_cvt_pk_bf16_f32 v176, v80, v81
	v_exp_f32_e32 v84, v84
	v_add_f32_e32 v169, v169, v82
	v_exp_f32_e32 v85, v85
	v_add_f32_e32 v169, v169, v83
	v_cvt_pk_bf16_f32 v177, v82, v83
	v_exp_f32_e32 v86, v86
	s_waitcnt lgkmcnt(5)
	v_mfma_f32_32x32x16_bf16 v[112:127], v[202:205], v[100:103], v[112:127]
	ds_read_b128 v[202:205], v175 offset:24576
	ds_read_b64_tr_b16 v[158:159], v143 offset:32768
	ds_read_b64_tr_b16 v[160:161], v143 offset:34816
	v_add_f32_e32 v169, v169, v84
	v_exp_f32_e32 v87, v87
	v_add_f32_e32 v169, v169, v85
	v_cvt_pk_bf16_f32 v178, v84, v85
	v_exp_f32_e32 v88, v88
	v_add_f32_e32 v169, v169, v86
	v_exp_f32_e32 v89, v89
	v_add_f32_e32 v169, v169, v87
	v_cvt_pk_bf16_f32 v179, v86, v87
	v_exp_f32_e32 v90, v90
	v_add_f32_e32 v169, v169, v88
	v_exp_f32_e32 v91, v91
	v_add_f32_e32 v169, v169, v89
	s_waitcnt lgkmcnt(7)
	v_mfma_f32_32x32x16_bf16 v[112:127], v[206:209], v[104:107], v[112:127]
	ds_read_b128 v[206:209], v210 offset:24576
	ds_read_b64_tr_b16 v[162:163], v146 offset:32768
	ds_read_b64_tr_b16 v[164:165], v146 offset:34816
	v_cvt_pk_bf16_f32 v180, v88, v89
	v_exp_f32_e32 v92, v92
	v_add_f32_e32 v169, v169, v90
	v_exp_f32_e32 v93, v93
	v_add_f32_e32 v169, v169, v91
	v_cvt_pk_bf16_f32 v181, v90, v91
	v_exp_f32_e32 v94, v94
	v_add_f32_e32 v169, v169, v92
	v_exp_f32_e32 v95, v95
	v_add_f32_e32 v169, v169, v93
	v_cvt_pk_bf16_f32 v182, v92, v93
	v_add_f32_e32 v169, v169, v94
	v_add_f32_e32 v169, v169, v95
	v_cvt_pk_bf16_f32 v183, v94, v95
	s_waitcnt lgkmcnt(9)
	v_mfma_f32_32x32x16_bf16 v[112:127], v[150:153], v[108:111], v[112:127]
	ds_read_b128 v[150:153], v211 offset:24576
	ds_read_b64_tr_b16 v[230:231], v147 offset:32768
	ds_read_b64_tr_b16 v[232:233], v147 offset:34816
	s_add_i32 s59, s59, 1
	s_nop 3
	s_waitcnt vmcnt(3) lgkmcnt(0)
	s_barrier
	s_add_i32 s71, s25, -6
	s_cmp_lt_i32 s59, s71
	s_cbranch_scc0 .Lcattn_tail

; __device__ __forceinline__ unsigned cvt_pk_bf16(float lo, float hi) { f32x2 v = {lo, hi}; bf16x2_t b = __builtin_convertvector(v, bf16x2_t); return __builtin_bit_cast(unsigned, b); }
; template <int DV>
; __device__ __forceinline__ void attn_pass(const int tid, unsigned char* smem, const bf16_t* Q0, int qpitch, const bf16_t* Kb, int kpitch, const bf16_t* Vb, int vpitch,
;                                           int b, int ntiles, float kmax, f32x16 (&o)[DV / 32], float& linv) {
;     ...
;     for (int kt = 0; kt < ntiles; ++kt) {
;         if (kt + 1 < ntiles) gload(kt + 1);
;         const unsigned char* Ks = smem + (kt & 1) * BUF; const unsigned char* Vs = Ks + KBYTES;
;         const unsigned char* kp = Ks + r32 * KP + hi * 16;
;         bf16x8 pf[2][2];
; #pragma unroll
;         for (int kb = 0; kb < 2; ++kb) {
;             f32x16 s;
; #pragma unroll
;             for (int r = 0; r < 16; ++r) s[r] = nshift;
; #pragma unroll
;             for (int ds = 0; ds < 4; ++ds) {
;                 const bf16x8 kf = *(const bf16x8*)(kp + kb * 32 * KP + ds * 32);
;                 s = __builtin_amdgcn_mfma_f32_32x32x16_bf16(kf, qf[ds], s, 0, 0, 0);
;             }
;             float ls = 0.f;
; #pragma unroll
;             for (int r = 0; r < 16; ++r) { s[r] = __builtin_amdgcn_exp2f(s[r]); ls += s[r]; }
;             lsum += ls;
; #pragma unroll
;             for (int j = 0; j < 2; ++j) {
;                 u32x4 w0;
;                 w0.x = cvt_pk_bf16(s[8 * j + 0], s[8 * j + 1]); w0.y = cvt_pk_bf16(s[8 * j + 2], s[8 * j + 3]); w0.z = cvt_pk_bf16(s[8 * j + 4], s[8 * j + 5]); w0.w = cvt_pk_bf16(s[8 * j + 6], s[8 * j + 7]);
;                 pf[kb][j] = __builtin_bit_cast(bf16x8, w0);
;             }
;         }
;         const unsigned char* vp = Vs + (4 * hi + q4) * VP + (16 * nhalf + 4 * p4) * 2;
; #pragma unroll
;         for (int d0 = 0; d0 < DV / 32; ++d0) {
; #pragma unroll
;             for (int kb = 0; kb < 2; ++kb)
; #pragma unroll
;                 for (int j = 0; j < 2; ++j) {
;                     const unsigned char* a = vp + (32 * kb + 16 * j) * VP + d0 * 64;
;                     const s16x4 lo = ld_tr(a), h4 = ld_tr(a + 8 * VP);
;                     const bf16x8 vf = (bf16x8){lo[0], lo[1], lo[2], lo[3], h4[0], h4[1], h4[2], h4[3]};
;                     o[d0] = __builtin_amdgcn_mfma_f32_32x32x16_bf16(vf, pf[kb][j], o[d0], 0, 0, 0);
;                 }
.Lcattn_tail:
	v_mfma_f32_32x32x16_bf16 v[80:95], v[198:201], v[96:99], v[32:47]
	ds_read_b128 v[198:201], v174 offset:28672
	v_exp_f32_e32 v112, v112
	v_exp_f32_e32 v113, v113
	v_exp_f32_e32 v114, v114
	v_mfma_f32_32x32x16_bf16 v[80:95], v[202:205], v[100:103], v[80:95]
	ds_read_b128 v[202:205], v175 offset:28672
	v_add_f32_e32 v169, v169, v112
	v_exp_f32_e32 v115, v115
	v_add_f32_e32 v169, v169, v113
	v_cvt_pk_bf16_f32 v184, v112, v113
	v_mfma_f32_32x32x16_bf16 v[80:95], v[206:209], v[104:107], v[80:95]
	ds_read_b128 v[206:209], v210 offset:28672
	v_exp_f32_e32 v116, v116
	v_add_f32_e32 v169, v169, v114
	v_exp_f32_e32 v117, v117
	v_mfma_f32_32x32x16_bf16 v[80:95], v[150:153], v[108:111], v[80:95]
	ds_read_b128 v[150:153], v211 offset:28672
	v_add_f32_e32 v169, v169, v115
	v_cvt_pk_bf16_f32 v185, v114, v115
	v_exp_f32_e32 v118, v118
	v_add_f32_e32 v169, v169, v116
	s_waitcnt lgkmcnt(10)
	v_mfma_f32_32x32x16_bf16 v[0:15], v[154:157], v[176:179], v[0:15]
	ds_read_b64_tr_b16 v[154:155], v142 offset:36864
	ds_read_b64_tr_b16 v[156:157], v142 offset:38912
	s_add_i32 s71, s25, -1
	s_add_i32 s70, s59, 3
	s_min_u32 s70, s70, s71
	s_cmp_lt_u32 s70, 4
	s_cselect_b32 s2, s65, s32
	s_lshl_b32 s3, s70, 6
	s_add_i32 s2, s2, s3
	s_lshl_b32 s2, s2, 10
	s_add_u32 s60, s66, s2
	s_addc_u32 s61, s67, 0
	s_add_i32 s70, s59, 2
	s_min_u32 s70, s70, s71
	s_cmp_lt_u32 s70, 4
	s_cselect_b32 s2, s65, s32
	s_lshl_b32 s3, s70, 6
	s_add_i32 s2, s2, s3
	s_lshl_b32 s2, s2, 10
	s_add_u32 s62, s68, s2
	s_addc_u32 s63, s69, 0
	v_exp_f32_e32 v119, v119
	v_add_f32_e32 v169, v169, v117
	v_cvt_pk_bf16_f32 v186, v116, v117
	v_exp_f32_e32 v120, v120
	s_waitcnt lgkmcnt(10)
	v_mfma_f32_32x32x16_bf16 v[16:31], v[158:161], v[176:179], v[16:31]
	ds_read_b64_tr_b16 v[158:159], v143 offset:36864
	ds_read_b64_tr_b16 v[160:161], v143 offset:38912
	s_mov_b32 m0, s56
	s_nop 0
	global_load_lds_dwordx4 v166, s[60:61]
	v_add_f32_e32 v169, v169, v118
	v_exp_f32_e32 v121, v121
	v_add_f32_e32 v169, v169, v119
	s_waitcnt lgkmcnt(10)
	v_mfma_f32_32x32x16_bf16 v[48:63], v[162:165], v[176:179], v[48:63]
	ds_read_b64_tr_b16 v[162:163], v146 offset:36864
	ds_read_b64_tr_b16 v[164:165], v146 offset:38912
	s_add_i32 m0, s56, 0x2000
	s_nop 0
	global_load_lds_dwordx4 v167, s[62:63]
	s_add_i32 m0, s56, 0x4000
	s_nop 0
	global_load_lds_dwordx4 v132, s[62:63]
	v_cvt_pk_bf16_f32 v187, v118, v119
	v_exp_f32_e32 v122, v122
	v_add_f32_e32 v169, v169, v120
	v_exp_f32_e32 v123, v123
	s_waitcnt lgkmcnt(10)
	v_mfma_f32_32x32x16_bf16 v[64:79], v[230:233], v[176:179], v[64:79]
	ds_read_b64_tr_b16 v[230:231], v147 offset:36864
	ds_read_b64_tr_b16 v[232:233], v147 offset:38912
	v_add_f32_e32 v169, v169, v121
	v_cvt_pk_bf16_f32 v188, v120, v121
	v_exp_f32_e32 v124, v124
	s_waitcnt lgkmcnt(6)
	v_mfma_f32_32x32x16_bf16 v[0:15], v[154:157], v[180:183], v[0:15]
	ds_read_b64_tr_b16 v[154:155], v142 offset:40960
	ds_read_b64_tr_b16 v[156:157], v142 offset:43008
	v_add_f32_e32 v169, v169, v122
	v_exp_f32_e32 v125, v125
	v_add_f32_e32 v169, v169, v123
	v_cvt_pk_bf16_f32 v189, v122, v123
	s_waitcnt lgkmcnt(6)
	v_mfma_f32_32x32x16_bf16 v[16:31], v[158:161], v[180:183], v[16:31]
	ds_read_b64_tr_b16 v[158:159], v143 offset:40960
	ds_read_b64_tr_b16 v[160:161], v143 offset:43008
	v_exp_f32_e32 v126, v126
	v_add_f32_e32 v169, v169, v124
	v_exp_f32_e32 v127, v127
	s_waitcnt lgkmcnt(6)
	v_mfma_f32_32x32x16_bf16 v[48:63], v[162:165], v[180:183], v[48:63]
	ds_read_b64_tr_b16 v[162:163], v146 offset:40960
	ds_read_b64_tr_b16 v[164:165], v146 offset:43008
	v_add_f32_e32 v169, v169, v125
	v_cvt_pk_bf16_f32 v190, v124, v125
	v_add_f32_e32 v169, v169, v126
	v_add_f32_e32 v169, v169, v127
	v_cvt_pk_bf16_f32 v191, v126, v127
	s_waitcnt lgkmcnt(6)
	v_mfma_f32_32x32x16_bf16 v[64:79], v[230:233], v[180:183], v[64:79]
	ds_read_b64_tr_b16 v[230:231], v147 offset:40960
	ds_read_b64_tr_b16 v[232:233], v147 offset:43008
	v_mfma_f32_32x32x16_bf16 v[112:127], v[198:201], v[96:99], v[32:47]
	ds_read_b128 v[198:201], v128
	v_exp_f32_e32 v80, v80
	v_exp_f32_e32 v81, v81
	v_exp_f32_e32 v82, v82
	v_mfma_f32_32x32x16_bf16 v[112:127], v[202:205], v[100:103], v[112:127]
	ds_read_b128 v[202:205], v129
	v_add_f32_e32 v169, v169, v80
	v_exp_f32_e32 v83, v83
	v_add_f32_e32 v169, v169, v81
	v_cvt_pk_bf16_f32 v176, v80, v81
	v_mfma_f32_32x32x16_bf16 v[112:127], v[206:209], v[104:107], v[112:127]
	ds_read_b128 v[206:209], v130
	v_exp_f32_e32 v84, v84
	v_add_f32_e32 v169, v169, v82
	v_exp_f32_e32 v85, v85
	v_mfma_f32_32x32x16_bf16 v[112:127], v[150:153], v[108:111], v[112:127]
	ds_read_b128 v[150:153], v131
	v_add_f32_e32 v169, v169, v83
	v_cvt_pk_bf16_f32 v177, v82, v83
	v_exp_f32_e32 v86, v86
	v_add_f32_e32 v169, v169, v84
	s_waitcnt lgkmcnt(10)
	v_mfma_f32_32x32x16_bf16 v[0:15], v[154:157], v[184:187], v[0:15]
	ds_read_b64_tr_b16 v[154:155], v142 offset:45056
	ds_read_b64_tr_b16 v[156:157], v142 offset:47104
	v_exp_f32_e32 v87, v87
	v_add_f32_e32 v169, v169, v85
	v_cvt_pk_bf16_f32 v178, v84, v85
	v_exp_f32_e32 v88, v88
	s_waitcnt lgkmcnt(10)
	v_mfma_f32_32x32x16_bf16 v[16:31], v[158:161], v[184:187], v[16:31]
	ds_read_b64_tr_b16 v[158:159], v143 offset:45056
	ds_read_b64_tr_b16 v[160:161], v143 offset:47104
	v_add_f32_e32 v169, v169, v86
	v_exp_f32_e32 v89, v89
	v_add_f32_e32 v169, v169, v87
	s_waitcnt lgkmcnt(10)
	v_mfma_f32_32x32x16_bf16 v[48:63], v[162:165], v[184:187], v[48:63]
	ds_read_b64_tr_b16 v[162:163], v146 offset:45056
	ds_read_b64_tr_b16 v[164:165], v146 offset:47104
	v_cvt_pk_bf16_f32 v179, v86, v87
	v_exp_f32_e32 v90, v90
	v_add_f32_e32 v169, v169, v88
	v_exp_f32_e32 v91, v91
	s_waitcnt lgkmcnt(10)
	v_mfma_f32_32x32x16_bf16 v[64:79], v[230:233], v[184:187], v[64:79]
	ds_read_b64_tr_b16 v[230:231], v147 offset:45056
	ds_read_b64_tr_b16 v[232:233], v147 offset:47104
	v_add_f32_e32 v169, v169, v89
	v_cvt_pk_bf16_f32 v180, v88, v89
	v_exp_f32_e32 v92, v92
	s_waitcnt lgkmcnt(6)
	v_mfma_f32_32x32x16_bf16 v[0:15], v[154:157], v[188:191], v[0:15]
	ds_read_b64_tr_b16 v[154:155], v170 offset:8192
	ds_read_b64_tr_b16 v[156:157], v170 offset:10240
	v_add_f32_e32 v169, v169, v90
	v_exp_f32_e32 v93, v93
	v_add_f32_e32 v169, v169, v91
	v_cvt_pk_bf16_f32 v181, v90, v91
	s_waitcnt lgkmcnt(6)
	v_mfma_f32_32x32x16_bf16 v[16:31], v[158:161], v[188:191], v[16:31]
	ds_read_b64_tr_b16 v[158:159], v171 offset:8192
	ds_read_b64_tr_b16 v[160:161], v171 offset:10240
	v_exp_f32_e32 v94, v94
	v_add_f32_e32 v169, v169, v92
	v_exp_f32_e32 v95, v95
	s_waitcnt lgkmcnt(6)
	v_mfma_f32_32x32x16_bf16 v[48:63], v[162:165], v[188:191], v[48:63]
	ds_read_b64_tr_b16 v[162:163], v172 offset:8192
	ds_read_b64_tr_b16 v[164:165], v172 offset:10240
	s_add_i32 s59, s59, 1
	v_add_f32_e32 v169, v169, v93
	v_cvt_pk_bf16_f32 v182, v92, v93
	v_add_f32_e32 v169, v169, v94
	v_add_f32_e32 v169, v169, v95
	v_cvt_pk_bf16_f32 v183, v94, v95
	s_waitcnt lgkmcnt(6)
	v_mfma_f32_32x32x16_bf16 v[64:79], v[230:233], v[188:191], v[64:79]
	ds_read_b64_tr_b16 v[230:231], v173 offset:8192
	ds_read_b64_tr_b16 v[232:233], v173 offset:10240
	s_waitcnt vmcnt(3) lgkmcnt(8)
	s_barrier
; __device__ __forceinline__ unsigned cvt_pk_bf16(float lo, float hi) { f32x2 v = {lo, hi}; bf16x2_t b = __builtin_convertvector(v, bf16x2_t); return __builtin_bit_cast(unsigned, b); }
; template <int DV>
; __device__ __forceinline__ void attn_pass(const int tid, unsigned char* smem, const bf16_t* Q0, int qpitch, const bf16_t* Kb, int kpitch, const bf16_t* Vb, int vpitch,
;                                           int b, int ntiles, float kmax, f32x16 (&o)[DV / 32], float& linv) {
;     ...
;     for (int kt = 0; kt < ntiles; ++kt) {
;         if (kt + 1 < ntiles) gload(kt + 1);
;         const unsigned char* Ks = smem + (kt & 1) * BUF; const unsigned char* Vs = Ks + KBYTES;
;         const unsigned char* kp = Ks + r32 * KP + hi * 16;
;         bf16x8 pf[2][2];
; #pragma unroll
;         for (int kb = 0; kb < 2; ++kb) {
;             f32x16 s;
; #pragma unroll
;             for (int r = 0; r < 16; ++r) s[r] = nshift;
; #pragma unroll
;             for (int ds = 0; ds < 4; ++ds) {
;                 const bf16x8 kf = *(const bf16x8*)(kp + kb * 32 * KP + ds * 32);
;                 s = __builtin_amdgcn_mfma_f32_32x32x16_bf16(kf, qf[ds], s, 0, 0, 0);
;             }
;             float ls = 0.f;
; #pragma unroll
;             for (int r = 0; r < 16; ++r) { s[r] = __builtin_amdgcn_exp2f(s[r]); ls += s[r]; }
;             lsum += ls;
; #pragma unroll
;             for (int j = 0; j < 2; ++j) {
;                 u32x4 w0;
;                 w0.x = cvt_pk_bf16(s[8 * j + 0], s[8 * j + 1]); w0.y = cvt_pk_bf16(s[8 * j + 2], s[8 * j + 3]); w0.z = cvt_pk_bf16(s[8 * j + 4], s[8 * j + 5]); w0.w = cvt_pk_bf16(s[8 * j + 6], s[8 * j + 7]);
;                 pf[kb][j] = __builtin_bit_cast(bf16x8, w0);
;             }
;         }
;         const unsigned char* vp = Vs + (4 * hi + q4) * VP + (16 * nhalf + 4 * p4) * 2;
; #pragma unroll
;         for (int d0 = 0; d0 < DV / 32; ++d0) {
; #pragma unroll
;             for (int kb = 0; kb < 2; ++kb)
; #pragma unroll
;                 for (int j = 0; j < 2; ++j) {
;                     const unsigned char* a = vp + (32 * kb + 16 * j) * VP + d0 * 64;
;                     const s16x4 lo = ld_tr(a), h4 = ld_tr(a + 8 * VP);
;                     const bf16x8 vf = (bf16x8){lo[0], lo[1], lo[2], lo[3], h4[0], h4[1], h4[2], h4[3]};
;                     o[d0] = __builtin_amdgcn_mfma_f32_32x32x16_bf16(vf, pf[kb][j], o[d0], 0, 0, 0);
;                 }
	v_mfma_f32_32x32x16_bf16 v[80:95], v[198:201], v[96:99], v[32:47]
	ds_read_b128 v[198:201], v128 offset:4096
	v_exp_f32_e32 v112, v112
	v_exp_f32_e32 v113, v113
	v_exp_f32_e32 v114, v114
	v_mfma_f32_32x32x16_bf16 v[80:95], v[202:205], v[100:103], v[80:95]
	ds_read_b128 v[202:205], v129 offset:4096
	v_add_f32_e32 v169, v169, v112
	v_exp_f32_e32 v115, v115
	v_add_f32_e32 v169, v169, v113
	v_cvt_pk_bf16_f32 v184, v112, v113
	v_mfma_f32_32x32x16_bf16 v[80:95], v[206:209], v[104:107], v[80:95]
	ds_read_b128 v[206:209], v130 offset:4096
	v_exp_f32_e32 v116, v116
	v_add_f32_e32 v169, v169, v114
	v_exp_f32_e32 v117, v117
	v_mfma_f32_32x32x16_bf16 v[80:95], v[150:153], v[108:111], v[80:95]
	ds_read_b128 v[150:153], v131 offset:4096
	v_add_f32_e32 v169, v169, v115
	v_cvt_pk_bf16_f32 v185, v114, v115
	v_exp_f32_e32 v118, v118
	v_add_f32_e32 v169, v169, v116
	s_waitcnt lgkmcnt(10)
	v_mfma_f32_32x32x16_bf16 v[0:15], v[154:157], v[176:179], v[0:15]
	ds_read_b64_tr_b16 v[154:155], v170 offset:12288
	ds_read_b64_tr_b16 v[156:157], v170 offset:14336
	s_add_i32 s71, s25, -1
	s_add_i32 s70, s59, 3
	s_min_u32 s70, s70, s71
	s_cmp_lt_u32 s70, 4
	s_cselect_b32 s2, s65, s32
	s_lshl_b32 s3, s70, 6
	s_add_i32 s2, s2, s3
	s_lshl_b32 s2, s2, 10
	s_add_u32 s60, s66, s2
	s_addc_u32 s61, s67, 0
	s_add_i32 s70, s59, 2
	s_min_u32 s70, s70, s71
	s_cmp_lt_u32 s70, 4
	s_cselect_b32 s2, s65, s32
	s_lshl_b32 s3, s70, 6
	s_add_i32 s2, s2, s3
	s_lshl_b32 s2, s2, 10
	s_add_u32 s62, s68, s2
	s_addc_u32 s63, s69, 0
	v_exp_f32_e32 v119, v119
	v_add_f32_e32 v169, v169, v117
	v_cvt_pk_bf16_f32 v186, v116, v117
	v_exp_f32_e32 v120, v120
	s_waitcnt lgkmcnt(10)
	v_mfma_f32_32x32x16_bf16 v[16:31], v[158:161], v[176:179], v[16:31]
	ds_read_b64_tr_b16 v[158:159], v171 offset:12288
	ds_read_b64_tr_b16 v[160:161], v171 offset:14336
	s_add_i32 m0, s56, 0x6000
	s_nop 0
	global_load_lds_dwordx4 v166, s[60:61]
	v_add_f32_e32 v169, v169, v118
	v_exp_f32_e32 v121, v121
	v_add_f32_e32 v169, v169, v119
	s_waitcnt lgkmcnt(10)
	v_mfma_f32_32x32x16_bf16 v[48:63], v[162:165], v[176:179], v[48:63]
	ds_read_b64_tr_b16 v[162:163], v172 offset:12288
	ds_read_b64_tr_b16 v[164:165], v172 offset:14336
	s_add_i32 m0, s56, 0x8000
	s_nop 0
	global_load_lds_dwordx4 v167, s[62:63]
	s_add_i32 m0, s56, 0xa000
	s_nop 0
	global_load_lds_dwordx4 v132, s[62:63]
	v_cvt_pk_bf16_f32 v187, v118, v119
	v_exp_f32_e32 v122, v122
	v_add_f32_e32 v169, v169, v120
	v_exp_f32_e32 v123, v123
	s_waitcnt lgkmcnt(10)
	v_mfma_f32_32x32x16_bf16 v[64:79], v[230:233], v[176:179], v[64:79]
	ds_read_b64_tr_b16 v[230:231], v173 offset:12288
	ds_read_b64_tr_b16 v[232:233], v173 offset:14336
	v_add_f32_e32 v169, v169, v121
	v_cvt_pk_bf16_f32 v188, v120, v121
	v_exp_f32_e32 v124, v124
	s_waitcnt lgkmcnt(6)
	v_mfma_f32_32x32x16_bf16 v[0:15], v[154:157], v[180:183], v[0:15]
	ds_read_b64_tr_b16 v[154:155], v170 offset:16384
	ds_read_b64_tr_b16 v[156:157], v170 offset:18432
	v_add_f32_e32 v169, v169, v122
	v_exp_f32_e32 v125, v125
	v_add_f32_e32 v169, v169, v123
	v_cvt_pk_bf16_f32 v189, v122, v123
	s_waitcnt lgkmcnt(6)
	v_mfma_f32_32x32x16_bf16 v[16:31], v[158:161], v[180:183], v[16:31]
	ds_read_b64_tr_b16 v[158:159], v171 offset:16384
	ds_read_b64_tr_b16 v[160:161], v171 offset:18432
	v_exp_f32_e32 v126, v126
	v_add_f32_e32 v169, v169, v124
	v_exp_f32_e32 v127, v127
	s_waitcnt lgkmcnt(6)
	v_mfma_f32_32x32x16_bf16 v[48:63], v[162:165], v[180:183], v[48:63]
	ds_read_b64_tr_b16 v[162:163], v172 offset:16384
	ds_read_b64_tr_b16 v[164:165], v172 offset:18432
	v_add_f32_e32 v169, v169, v125
	v_cvt_pk_bf16_f32 v190, v124, v125
	v_add_f32_e32 v169, v169, v126
	v_add_f32_e32 v169, v169, v127
	v_cvt_pk_bf16_f32 v191, v126, v127
	s_waitcnt lgkmcnt(6)
	v_mfma_f32_32x32x16_bf16 v[64:79], v[230:233], v[180:183], v[64:79]
	ds_read_b64_tr_b16 v[230:231], v173 offset:16384
	ds_read_b64_tr_b16 v[232:233], v173 offset:18432
	v_mfma_f32_32x32x16_bf16 v[112:127], v[198:201], v[96:99], v[32:47]
	ds_read_b128 v[198:201], v128 offset:24576
	v_exp_f32_e32 v80, v80
	v_exp_f32_e32 v81, v81
	v_exp_f32_e32 v82, v82
	v_mfma_f32_32x32x16_bf16 v[112:127], v[202:205], v[100:103], v[112:127]
	ds_read_b128 v[202:205], v129 offset:24576
	v_add_f32_e32 v169, v169, v80
	v_exp_f32_e32 v83, v83
	v_add_f32_e32 v169, v169, v81
	v_cvt_pk_bf16_f32 v176, v80, v81
	v_mfma_f32_32x32x16_bf16 v[112:127], v[206:209], v[104:107], v[112:127]
	ds_read_b128 v[206:209], v130 offset:24576
	v_exp_f32_e32 v84, v84
	v_add_f32_e32 v169, v169, v82
	v_exp_f32_e32 v85, v85
	v_mfma_f32_32x32x16_bf16 v[112:127], v[150:153], v[108:111], v[112:127]
	ds_read_b128 v[150:153], v131 offset:24576
	v_add_f32_e32 v169, v169, v83
	v_cvt_pk_bf16_f32 v177, v82, v83
	v_exp_f32_e32 v86, v86
	v_add_f32_e32 v169, v169, v84
	s_waitcnt lgkmcnt(10)
	v_mfma_f32_32x32x16_bf16 v[0:15], v[154:157], v[184:187], v[0:15]
	ds_read_b64_tr_b16 v[154:155], v170 offset:20480
	ds_read_b64_tr_b16 v[156:157], v170 offset:22528
	v_exp_f32_e32 v87, v87
	v_add_f32_e32 v169, v169, v85
	v_cvt_pk_bf16_f32 v178, v84, v85
	v_exp_f32_e32 v88, v88
	s_waitcnt lgkmcnt(10)
	v_mfma_f32_32x32x16_bf16 v[16:31], v[158:161], v[184:187], v[16:31]
	ds_read_b64_tr_b16 v[158:159], v171 offset:20480
	ds_read_b64_tr_b16 v[160:161], v171 offset:22528
	v_add_f32_e32 v169, v169, v86
	v_exp_f32_e32 v89, v89
	v_add_f32_e32 v169, v169, v87
	s_waitcnt lgkmcnt(10)
	v_mfma_f32_32x32x16_bf16 v[48:63], v[162:165], v[184:187], v[48:63]
	ds_read_b64_tr_b16 v[162:163], v172 offset:20480
	ds_read_b64_tr_b16 v[164:165], v172 offset:22528
	v_cvt_pk_bf16_f32 v179, v86, v87
	v_exp_f32_e32 v90, v90
	v_add_f32_e32 v169, v169, v88
	v_exp_f32_e32 v91, v91
	s_waitcnt lgkmcnt(10)
; __device__ __forceinline__ unsigned cvt_pk_bf16(float lo, float hi) { f32x2 v = {lo, hi}; bf16x2_t b = __builtin_convertvector(v, bf16x2_t); return __builtin_bit_cast(unsigned, b); }
; template <int DV>
; __device__ __forceinline__ void attn_pass(const int tid, unsigned char* smem, const bf16_t* Q0, int qpitch, const bf16_t* Kb, int kpitch, const bf16_t* Vb, int vpitch,
;                                           int b, int ntiles, float kmax, f32x16 (&o)[DV / 32], float& linv) {
;     ...
;     for (int kt = 0; kt < ntiles; ++kt) {
;         if (kt + 1 < ntiles) gload(kt + 1);
;         const unsigned char* Ks = smem + (kt & 1) * BUF; const unsigned char* Vs = Ks + KBYTES;
;         const unsigned char* kp = Ks + r32 * KP + hi * 16;
;         bf16x8 pf[2][2];
; #pragma unroll
;         for (int kb = 0; kb < 2; ++kb) {
;             f32x16 s;
; #pragma unroll
;             for (int r = 0; r < 16; ++r) s[r] = nshift;
; #pragma unroll
;             for (int ds = 0; ds < 4; ++ds) {
;                 const bf16x8 kf = *(const bf16x8*)(kp + kb * 32 * KP + ds * 32);
;                 s = __builtin_amdgcn_mfma_f32_32x32x16_bf16(kf, qf[ds], s, 0, 0, 0);
;             }
;             float ls = 0.f;
; #pragma unroll
;             for (int r = 0; r < 16; ++r) { s[r] = __builtin_amdgcn_exp2f(s[r]); ls += s[r]; }
;             lsum += ls;
; #pragma unroll
;             for (int j = 0; j < 2; ++j) {
;                 u32x4 w0;
;                 w0.x = cvt_pk_bf16(s[8 * j + 0], s[8 * j + 1]); w0.y = cvt_pk_bf16(s[8 * j + 2], s[8 * j + 3]); w0.z = cvt_pk_bf16(s[8 * j + 4], s[8 * j + 5]); w0.w = cvt_pk_bf16(s[8 * j + 6], s[8 * j + 7]);
;                 pf[kb][j] = __builtin_bit_cast(bf16x8, w0);
;             }
;         }
;         const unsigned char* vp = Vs + (4 * hi + q4) * VP + (16 * nhalf + 4 * p4) * 2;
; #pragma unroll
;         for (int d0 = 0; d0 < DV / 32; ++d0) {
; #pragma unroll
;             for (int kb = 0; kb < 2; ++kb)
; #pragma unroll
;                 for (int j = 0; j < 2; ++j) {
;                     const unsigned char* a = vp + (32 * kb + 16 * j) * VP + d0 * 64;
;                     const s16x4 lo = ld_tr(a), h4 = ld_tr(a + 8 * VP);
;                     const bf16x8 vf = (bf16x8){lo[0], lo[1], lo[2], lo[3], h4[0], h4[1], h4[2], h4[3]};
;                     o[d0] = __builtin_amdgcn_mfma_f32_32x32x16_bf16(vf, pf[kb][j], o[d0], 0, 0, 0);
;                 }
	v_mfma_f32_32x32x16_bf16 v[64:79], v[230:233], v[184:187], v[64:79]
	ds_read_b64_tr_b16 v[230:231], v173 offset:20480
	ds_read_b64_tr_b16 v[232:233], v173 offset:22528
	v_add_f32_e32 v169, v169, v89
	v_cvt_pk_bf16_f32 v180, v88, v89
	v_exp_f32_e32 v92, v92
	s_waitcnt lgkmcnt(6)
	v_mfma_f32_32x32x16_bf16 v[0:15], v[154:157], v[188:191], v[0:15]
	ds_read_b64_tr_b16 v[154:155], v170 offset:32768
	ds_read_b64_tr_b16 v[156:157], v170 offset:34816
	v_add_f32_e32 v169, v169, v90
	v_exp_f32_e32 v93, v93
	v_add_f32_e32 v169, v169, v91
	v_cvt_pk_bf16_f32 v181, v90, v91
	s_waitcnt lgkmcnt(6)
	v_mfma_f32_32x32x16_bf16 v[16:31], v[158:161], v[188:191], v[16:31]
	ds_read_b64_tr_b16 v[158:159], v171 offset:32768
	ds_read_b64_tr_b16 v[160:161], v171 offset:34816
	v_exp_f32_e32 v94, v94
	v_add_f32_e32 v169, v169, v92
	v_exp_f32_e32 v95, v95
	s_waitcnt lgkmcnt(6)
	v_mfma_f32_32x32x16_bf16 v[48:63], v[162:165], v[188:191], v[48:63]
	ds_read_b64_tr_b16 v[162:163], v172 offset:32768
	ds_read_b64_tr_b16 v[164:165], v172 offset:34816
	s_add_i32 s59, s59, 1
	v_add_f32_e32 v169, v169, v93
	v_cvt_pk_bf16_f32 v182, v92, v93
	v_add_f32_e32 v169, v169, v94
	v_add_f32_e32 v169, v169, v95
	v_cvt_pk_bf16_f32 v183, v94, v95
	s_waitcnt lgkmcnt(6)
	v_mfma_f32_32x32x16_bf16 v[64:79], v[230:233], v[188:191], v[64:79]
	ds_read_b64_tr_b16 v[230:231], v173 offset:32768
	ds_read_b64_tr_b16 v[232:233], v173 offset:34816
	s_waitcnt vmcnt(3) lgkmcnt(8)
	s_barrier
	v_mfma_f32_32x32x16_bf16 v[80:95], v[198:201], v[96:99], v[32:47]
	ds_read_b128 v[198:201], v128 offset:28672
	v_exp_f32_e32 v112, v112
	v_exp_f32_e32 v113, v113
	v_exp_f32_e32 v114, v114
	v_mfma_f32_32x32x16_bf16 v[80:95], v[202:205], v[100:103], v[80:95]
	ds_read_b128 v[202:205], v129 offset:28672
	v_add_f32_e32 v169, v169, v112
	v_exp_f32_e32 v115, v115
	v_add_f32_e32 v169, v169, v113
	v_cvt_pk_bf16_f32 v184, v112, v113
	v_mfma_f32_32x32x16_bf16 v[80:95], v[206:209], v[104:107], v[80:95]
	ds_read_b128 v[206:209], v130 offset:28672
	v_exp_f32_e32 v116, v116
	v_add_f32_e32 v169, v169, v114
	v_exp_f32_e32 v117, v117
	v_mfma_f32_32x32x16_bf16 v[80:95], v[150:153], v[108:111], v[80:95]
	ds_read_b128 v[150:153], v131 offset:28672
	v_add_f32_e32 v169, v169, v115
	v_cvt_pk_bf16_f32 v185, v114, v115
	v_exp_f32_e32 v118, v118
	v_add_f32_e32 v169, v169, v116
	s_waitcnt lgkmcnt(10)
	v_mfma_f32_32x32x16_bf16 v[0:15], v[154:157], v[176:179], v[0:15]
	ds_read_b64_tr_b16 v[154:155], v170 offset:36864
	ds_read_b64_tr_b16 v[156:157], v170 offset:38912
	v_exp_f32_e32 v119, v119
	v_add_f32_e32 v169, v169, v117
	v_cvt_pk_bf16_f32 v186, v116, v117
	v_exp_f32_e32 v120, v120
	s_waitcnt lgkmcnt(10)
	v_mfma_f32_32x32x16_bf16 v[16:31], v[158:161], v[176:179], v[16:31]
	ds_read_b64_tr_b16 v[158:159], v171 offset:36864
	ds_read_b64_tr_b16 v[160:161], v171 offset:38912
	v_add_f32_e32 v169, v169, v118
	v_exp_f32_e32 v121, v121
	v_add_f32_e32 v169, v169, v119
	s_waitcnt lgkmcnt(10)
	v_mfma_f32_32x32x16_bf16 v[48:63], v[162:165], v[176:179], v[48:63]
	ds_read_b64_tr_b16 v[162:163], v172 offset:36864
	ds_read_b64_tr_b16 v[164:165], v172 offset:38912
	v_cvt_pk_bf16_f32 v187, v118, v119
	v_exp_f32_e32 v122, v122
	v_add_f32_e32 v169, v169, v120
	v_exp_f32_e32 v123, v123
	s_waitcnt lgkmcnt(10)
	v_mfma_f32_32x32x16_bf16 v[64:79], v[230:233], v[176:179], v[64:79]
	ds_read_b64_tr_b16 v[230:231], v173 offset:36864
	ds_read_b64_tr_b16 v[232:233], v173 offset:38912
	v_add_f32_e32 v169, v169, v121
	v_cvt_pk_bf16_f32 v188, v120, v121
	v_exp_f32_e32 v124, v124
	s_waitcnt lgkmcnt(6)
	v_mfma_f32_32x32x16_bf16 v[0:15], v[154:157], v[180:183], v[0:15]
	ds_read_b64_tr_b16 v[154:155], v170 offset:40960
	ds_read_b64_tr_b16 v[156:157], v170 offset:43008
	v_add_f32_e32 v169, v169, v122
	v_exp_f32_e32 v125, v125
	v_add_f32_e32 v169, v169, v123
	v_cvt_pk_bf16_f32 v189, v122, v123
	s_waitcnt lgkmcnt(6)
	v_mfma_f32_32x32x16_bf16 v[16:31], v[158:161], v[180:183], v[16:31]
	ds_read_b64_tr_b16 v[158:159], v171 offset:40960
	ds_read_b64_tr_b16 v[160:161], v171 offset:43008
	v_exp_f32_e32 v126, v126
	v_add_f32_e32 v169, v169, v124
	v_exp_f32_e32 v127, v127
	s_waitcnt lgkmcnt(6)
	v_mfma_f32_32x32x16_bf16 v[48:63], v[162:165], v[180:183], v[48:63]
	ds_read_b64_tr_b16 v[162:163], v172 offset:40960
	ds_read_b64_tr_b16 v[164:165], v172 offset:43008
	v_add_f32_e32 v169, v169, v125
	v_cvt_pk_bf16_f32 v190, v124, v125
	v_add_f32_e32 v169, v169, v126
	v_add_f32_e32 v169, v169, v127
	v_cvt_pk_bf16_f32 v191, v126, v127
	s_waitcnt lgkmcnt(6)
	v_mfma_f32_32x32x16_bf16 v[64:79], v[230:233], v[180:183], v[64:79]
	ds_read_b64_tr_b16 v[230:231], v173 offset:40960
	ds_read_b64_tr_b16 v[232:233], v173 offset:43008
	v_mfma_f32_32x32x16_bf16 v[112:127], v[198:201], v[96:99], v[32:47]
	v_exp_f32_e32 v80, v80
	v_exp_f32_e32 v81, v81
	v_exp_f32_e32 v82, v82
	v_mfma_f32_32x32x16_bf16 v[112:127], v[202:205], v[100:103], v[112:127]
	v_add_f32_e32 v169, v169, v80
	v_exp_f32_e32 v83, v83
	v_add_f32_e32 v169, v169, v81
	v_cvt_pk_bf16_f32 v176, v80, v81
	v_mfma_f32_32x32x16_bf16 v[112:127], v[206:209], v[104:107], v[112:127]
	v_exp_f32_e32 v84, v84
	v_add_f32_e32 v169, v169, v82
	v_exp_f32_e32 v85, v85
	v_mfma_f32_32x32x16_bf16 v[112:127], v[150:153], v[108:111], v[112:127]
	v_add_f32_e32 v169, v169, v83
	v_cvt_pk_bf16_f32 v177, v82, v83
	v_exp_f32_e32 v86, v86
	v_add_f32_e32 v169, v169, v84
	s_waitcnt lgkmcnt(6)
	v_mfma_f32_32x32x16_bf16 v[0:15], v[154:157], v[184:187], v[0:15]
	ds_read_b64_tr_b16 v[154:155], v170 offset:45056
	ds_read_b64_tr_b16 v[156:157], v170 offset:47104
	v_exp_f32_e32 v87, v87
	v_add_f32_e32 v169, v169, v85
	v_cvt_pk_bf16_f32 v178, v84, v85
	v_exp_f32_e32 v88, v88
	s_waitcnt lgkmcnt(6)
; template <int DV>
; __device__ __forceinline__ void attn_pass(const int tid, unsigned char* smem, const bf16_t* Q0, int qpitch, const bf16_t* Kb, int kpitch, const bf16_t* Vb, int vpitch,
;                                           int b, int ntiles, float kmax, f32x16 (&o)[DV / 32], float& linv) {
;     ...
;     for (int kt = 0; kt < ntiles; ++kt) {
;         if (kt + 1 < ntiles) gload(kt + 1);
;         const unsigned char* Ks = smem + (kt & 1) * BUF; const unsigned char* Vs = Ks + KBYTES;
;         const unsigned char* kp = Ks + r32 * KP + hi * 16;
;         bf16x8 pf[2][2];
; #pragma unroll
;         for (int kb = 0; kb < 2; ++kb) {
;             f32x16 s;
; #pragma unroll
;             for (int r = 0; r < 16; ++r) s[r] = nshift;
; #pragma unroll
;             for (int ds = 0; ds < 4; ++ds) {
;                 const bf16x8 kf = *(const bf16x8*)(kp + kb * 32 * KP + ds * 32);
;                 s = __builtin_amdgcn_mfma_f32_32x32x16_bf16(kf, qf[ds], s, 0, 0, 0);
;             }
;             float ls = 0.f;
; #pragma unroll
;             for (int r = 0; r < 16; ++r) { s[r] = __builtin_amdgcn_exp2f(s[r]); ls += s[r]; }
;             lsum += ls;
; #pragma unroll
;             for (int j = 0; j < 2; ++j) {
;                 u32x4 w0;
;                 w0.x = cvt_pk_bf16(s[8 * j + 0], s[8 * j + 1]); w0.y = cvt_pk_bf16(s[8 * j + 2], s[8 * j + 3]); w0.z = cvt_pk_bf16(s[8 * j + 4], s[8 * j + 5]); w0.w = cvt_pk_bf16(s[8 * j + 6], s[8 * j + 7]);
;                 pf[kb][j] = __builtin_bit_cast(bf16x8, w0);
;             }
;         }
;         const unsigned char* vp = Vs + (4 * hi + q4) * VP + (16 * nhalf + 4 * p4) * 2;
; #pragma unroll
;         for (int d0 = 0; d0 < DV / 32; ++d0) {
; #pragma unroll
;             for (int kb = 0; kb < 2; ++kb)
; #pragma unroll
;                 for (int j = 0; j < 2; ++j) {
;                     const unsigned char* a = vp + (32 * kb + 16 * j) * VP + d0 * 64;
;                     const s16x4 lo = ld_tr(a), h4 = ld_tr(a + 8 * VP);
;                     const bf16x8 vf = (bf16x8){lo[0], lo[1], lo[2], lo[3], h4[0], h4[1], h4[2], h4[3]};
;                     o[d0] = __builtin_amdgcn_mfma_f32_32x32x16_bf16(vf, pf[kb][j], o[d0], 0, 0, 0);
;                 }
;             if (d0 & 1) __builtin_amdgcn_sched_barrier(0);
;         }
;         if (kt + 1 < ntiles) lwrite((kt + 1) & 1);
;         __syncthreads();
;     }
	v_mfma_f32_32x32x16_bf16 v[16:31], v[158:161], v[184:187], v[16:31]
	ds_read_b64_tr_b16 v[158:159], v171 offset:45056
	ds_read_b64_tr_b16 v[160:161], v171 offset:47104
	v_add_f32_e32 v169, v169, v86
	v_exp_f32_e32 v89, v89
	v_add_f32_e32 v169, v169, v87
	s_waitcnt lgkmcnt(6)
	v_mfma_f32_32x32x16_bf16 v[48:63], v[162:165], v[184:187], v[48:63]
	ds_read_b64_tr_b16 v[162:163], v172 offset:45056
	ds_read_b64_tr_b16 v[164:165], v172 offset:47104
	v_cvt_pk_bf16_f32 v179, v86, v87
	v_exp_f32_e32 v90, v90
	v_add_f32_e32 v169, v169, v88
	v_exp_f32_e32 v91, v91
	s_waitcnt lgkmcnt(6)
	v_mfma_f32_32x32x16_bf16 v[64:79], v[230:233], v[184:187], v[64:79]
	ds_read_b64_tr_b16 v[230:231], v173 offset:45056
	ds_read_b64_tr_b16 v[232:233], v173 offset:47104
	v_add_f32_e32 v169, v169, v89
	v_cvt_pk_bf16_f32 v180, v88, v89
	v_exp_f32_e32 v92, v92
	s_waitcnt lgkmcnt(6)
	v_mfma_f32_32x32x16_bf16 v[0:15], v[154:157], v[188:191], v[0:15]
	ds_read_b64_tr_b16 v[154:155], v142 offset:8192
	ds_read_b64_tr_b16 v[156:157], v142 offset:10240
	v_add_f32_e32 v169, v169, v90
	v_exp_f32_e32 v93, v93
	v_add_f32_e32 v169, v169, v91
	v_cvt_pk_bf16_f32 v181, v90, v91
	s_waitcnt lgkmcnt(6)
	v_mfma_f32_32x32x16_bf16 v[16:31], v[158:161], v[188:191], v[16:31]
	ds_read_b64_tr_b16 v[158:159], v143 offset:8192
	ds_read_b64_tr_b16 v[160:161], v143 offset:10240
	v_exp_f32_e32 v94, v94
	v_add_f32_e32 v169, v169, v92
	v_exp_f32_e32 v95, v95
	s_waitcnt lgkmcnt(6)
	v_mfma_f32_32x32x16_bf16 v[48:63], v[162:165], v[188:191], v[48:63]
	ds_read_b64_tr_b16 v[162:163], v146 offset:8192
	ds_read_b64_tr_b16 v[164:165], v146 offset:10240
	s_add_i32 s59, s59, 1
	v_add_f32_e32 v169, v169, v93
	v_cvt_pk_bf16_f32 v182, v92, v93
	v_add_f32_e32 v169, v169, v94
	v_add_f32_e32 v169, v169, v95
	v_cvt_pk_bf16_f32 v183, v94, v95
	s_waitcnt lgkmcnt(6)
	v_mfma_f32_32x32x16_bf16 v[64:79], v[230:233], v[188:191], v[64:79]
	ds_read_b64_tr_b16 v[230:231], v147 offset:8192
	ds_read_b64_tr_b16 v[232:233], v147 offset:10240
	s_waitcnt lgkmcnt(8)
	s_barrier
	s_waitcnt lgkmcnt(6)
	v_mfma_f32_32x32x16_bf16 v[0:15], v[154:157], v[176:179], v[0:15]
	ds_read_b64_tr_b16 v[154:155], v142 offset:12288
	ds_read_b64_tr_b16 v[156:157], v142 offset:14336
	v_exp_f32_e32 v112, v112
	v_exp_f32_e32 v113, v113
	v_exp_f32_e32 v114, v114
	v_add_f32_e32 v169, v169, v112
	v_exp_f32_e32 v115, v115
	s_waitcnt lgkmcnt(6)
	v_mfma_f32_32x32x16_bf16 v[16:31], v[158:161], v[176:179], v[16:31]
	ds_read_b64_tr_b16 v[158:159], v143 offset:12288
	ds_read_b64_tr_b16 v[160:161], v143 offset:14336
	v_add_f32_e32 v169, v169, v113
	v_cvt_pk_bf16_f32 v184, v112, v113
	v_exp_f32_e32 v116, v116
	v_add_f32_e32 v169, v169, v114
	v_exp_f32_e32 v117, v117
	s_waitcnt lgkmcnt(6)
	v_mfma_f32_32x32x16_bf16 v[48:63], v[162:165], v[176:179], v[48:63]
	ds_read_b64_tr_b16 v[162:163], v146 offset:12288
	ds_read_b64_tr_b16 v[164:165], v146 offset:14336
	v_add_f32_e32 v169, v169, v115
	v_cvt_pk_bf16_f32 v185, v114, v115
	v_exp_f32_e32 v118, v118
	v_add_f32_e32 v169, v169, v116
	v_exp_f32_e32 v119, v119
	v_add_f32_e32 v169, v169, v117
	s_waitcnt lgkmcnt(6)
	v_mfma_f32_32x32x16_bf16 v[64:79], v[230:233], v[176:179], v[64:79]
	ds_read_b64_tr_b16 v[230:231], v147 offset:12288
	ds_read_b64_tr_b16 v[232:233], v147 offset:14336
	v_cvt_pk_bf16_f32 v186, v116, v117
	v_exp_f32_e32 v120, v120
	v_add_f32_e32 v169, v169, v118
	v_exp_f32_e32 v121, v121
	v_add_f32_e32 v169, v169, v119
	v_cvt_pk_bf16_f32 v187, v118, v119
	s_waitcnt lgkmcnt(6)
	v_mfma_f32_32x32x16_bf16 v[0:15], v[154:157], v[180:183], v[0:15]
	ds_read_b64_tr_b16 v[154:155], v142 offset:16384
	ds_read_b64_tr_b16 v[156:157], v142 offset:18432
	v_exp_f32_e32 v122, v122
	v_add_f32_e32 v169, v169, v120
	v_exp_f32_e32 v123, v123
	v_add_f32_e32 v169, v169, v121
	v_cvt_pk_bf16_f32 v188, v120, v121
	v_exp_f32_e32 v124, v124
	s_waitcnt lgkmcnt(6)
	v_mfma_f32_32x32x16_bf16 v[16:31], v[158:161], v[180:183], v[16:31]
	ds_read_b64_tr_b16 v[158:159], v143 offset:16384
	ds_read_b64_tr_b16 v[160:161], v143 offset:18432
	v_add_f32_e32 v169, v169, v122
	v_exp_f32_e32 v125, v125
	v_add_f32_e32 v169, v169, v123
	v_cvt_pk_bf16_f32 v189, v122, v123
	v_exp_f32_e32 v126, v126
	s_waitcnt lgkmcnt(6)
	v_mfma_f32_32x32x16_bf16 v[48:63], v[162:165], v[180:183], v[48:63]
	ds_read_b64_tr_b16 v[162:163], v146 offset:16384
	ds_read_b64_tr_b16 v[164:165], v146 offset:18432
	v_add_f32_e32 v169, v169, v124
	v_exp_f32_e32 v127, v127
	v_add_f32_e32 v169, v169, v125
	v_cvt_pk_bf16_f32 v190, v124, v125
	v_add_f32_e32 v169, v169, v126
	v_add_f32_e32 v169, v169, v127
	v_cvt_pk_bf16_f32 v191, v126, v127
	s_waitcnt lgkmcnt(6)
	v_mfma_f32_32x32x16_bf16 v[64:79], v[230:233], v[180:183], v[64:79]
	ds_read_b64_tr_b16 v[230:231], v147 offset:16384
	ds_read_b64_tr_b16 v[232:233], v147 offset:18432
	s_waitcnt lgkmcnt(6)
	v_mfma_f32_32x32x16_bf16 v[0:15], v[154:157], v[184:187], v[0:15]
	ds_read_b64_tr_b16 v[154:155], v142 offset:20480
	ds_read_b64_tr_b16 v[156:157], v142 offset:22528
	s_waitcnt lgkmcnt(6)
	v_mfma_f32_32x32x16_bf16 v[16:31], v[158:161], v[184:187], v[16:31]
	ds_read_b64_tr_b16 v[158:159], v143 offset:20480
	ds_read_b64_tr_b16 v[160:161], v143 offset:22528
	s_waitcnt lgkmcnt(6)
	v_mfma_f32_32x32x16_bf16 v[48:63], v[162:165], v[184:187], v[48:63]
	ds_read_b64_tr_b16 v[162:163], v146 offset:20480
	ds_read_b64_tr_b16 v[164:165], v146 offset:22528
	s_waitcnt lgkmcnt(6)
	v_mfma_f32_32x32x16_bf16 v[64:79], v[230:233], v[184:187], v[64:79]
	ds_read_b64_tr_b16 v[230:231], v147 offset:20480
	ds_read_b64_tr_b16 v[232:233], v147 offset:22528
	s_waitcnt lgkmcnt(6)
	v_mfma_f32_32x32x16_bf16 v[0:15], v[154:157], v[188:191], v[0:15]
	s_waitcnt lgkmcnt(4)
	v_mfma_f32_32x32x16_bf16 v[16:31], v[158:161], v[188:191], v[16:31]
	s_waitcnt lgkmcnt(2)
	v_mfma_f32_32x32x16_bf16 v[48:63], v[162:165], v[188:191], v[48:63]
	s_waitcnt lgkmcnt(0)
	v_mfma_f32_32x32x16_bf16 v[64:79], v[230:233], v[188:191], v[64:79]
	s_waitcnt lgkmcnt(0)
	s_barrier
	s_waitcnt vmcnt(0)
	s_setprio 0

; __device__ __forceinline__ float bf2f(unsigned short b) { return __uint_as_float((unsigned)b << 16); }
; __device__ __forceinline__ float sum_x32(float v) { auto rr = __builtin_amdgcn_permlane32_swap(__float_as_uint(v), __float_as_uint(v), false, false); return __uint_as_float(rr[0]) + __uint_as_float(rr[1]); }
; __device__ __forceinline__ void attn_pass_A2(const int tid, unsigned char* smem, const bf16_t* Q0w, int qpitch, const bf16_t* Kb, int kpitch, const bf16_t* Vb, int vpitch,
;                                              int b, int ntiles, float kmax, f32x16 (&o)[2][2], float (&linv)[2]) {
;     constexpr int KP = 144, VP = 192, KBYTES = 64 * KP, VBYTES = 64 * VP, BUF = KBYTES + VBYTES;
;     const int lane = tid & 63, r32 = lane & 31, hi = lane >> 5;
;     float nshift[2], lsum[2] = {0.f, 0.f};
;     unsigned char* qs = smem + 2 * BUF + ((tid >> 6) * 64 + r32) * KP + hi * 16;
; #pragma unroll
;     for (int qb = 0; qb < 2; ++qb) {
;         const bf16_t* qp = Q0w + (size_t)(32 * qb + r32) * qpitch + 8 * hi; float ssq = 0.f;
; #pragma unroll
;         for (int ds = 0; ds < 4; ++ds) { const bf16x8 qv = *(const bf16x8*)(qp + 16 * ds); *(bf16x8*)(qs + qb * 32 * KP + ds * 32) = qv;
; #pragma unroll
;             for (int j = 0; j < 8; ++j) { const float f = bf2f((unsigned short)qv[j]); ssq += f * f; } }
;         nshift[qb] = -sqrtf(sum_x32(ssq)) * kmax;
; #pragma unroll
;         for (int d0 = 0; d0 < 2; ++d0)
; #pragma unroll
;             for (int r = 0; r < 16; ++r) o[qb][d0][r] = 0.f;
;     }
.LBB0_417:
	s_and_b64 vcc, exec, s[0:1]
	s_cbranch_vccz .LBB0_394
	s_and_b32 s0, s27, 0xffffffc0
	s_add_i32 s1, s0, 0xffffff00
	s_cmp_lt_i32 s0, s11
	s_cselect_b32 s0, s0, s1
	s_ashr_i32 s1, s0, 31
	s_add_u32 s0, s8, s0
	s_addc_u32 s1, s9, s1
	s_lshl_b64 s[0:1], s[0:1], 11
	v_readlane_b32 s2, v253, 22
	v_readlane_b32 s3, v253, 23
	s_add_u32 s2, s2, s0
	s_addc_u32 s3, s3, s1
	s_lshl_b32 s0, s26, 6
	s_ashr_i32 s1, s0, 31
	s_lshl_b64 s[12:13], s[0:1], 1
	s_add_u32 s0, s2, s12
	s_addc_u32 s1, s3, s13
	v_mov_b32_e32 v139, v193
	v_lshl_add_u64 v[0:1], s[0:1], 0, v[138:139]
	v_lshlrev_b32_e32 v192, 11, v218
	v_lshl_add_u64 v[0:1], v[0:1], 0, v[192:193]
	global_load_dwordx4 v[20:23], v[0:1], off
	global_load_dwordx4 v[24:27], v[0:1], off offset:32
	global_load_dwordx4 v[28:31], v[0:1], off offset:64
	global_load_dwordx4 v[32:35], v[0:1], off offset:96
	s_mov_b32 s0, 0x10000
	v_add_co_u32_e32 v10, vcc, s0, v0
	s_movk_i32 s0, 0x90
	s_nop 0
	v_addc_co_u32_e32 v11, vcc, 0, v1, vcc
	global_load_dwordx4 v[16:19], v[10:11], off
	v_and_b32_e32 v1, 0xfffffdf, v197
	v_mul_lo_u32 v1, v1, s0
	v_add_u32_e32 v1, 0, v1
	v_add_u32_e32 v139, v1, v138
	global_load_dwordx4 v[2:5], v[10:11], off offset:32
	global_load_dwordx4 v[6:9], v[10:11], off offset:64
	s_nop 0
	global_load_dwordx4 v[10:13], v[10:11], off offset:96
	s_lshl_b32 s0, s26, 4
	s_andn2_b32 s0, s0, 63
	s_ashr_i32 s1, s0, 31
	s_lshl_b64 s[0:1], s[0:1], 1
	v_readlane_b32 s2, v251, 33
	s_add_u32 s14, s2, s0
	v_readlane_b32 s2, v251, 34
	s_addc_u32 s15, s2, s1
	v_readlane_b32 s2, v251, 35
	s_add_u32 s16, s2, s0
	s_mov_b32 s2, 0xf800000
	v_readlane_b32 s0, v251, 36
	s_addc_u32 s17, s0, s1
	v_and_b32_e32 v192, 0x70, v217
	v_mov_b32_e32 v0, 0
	s_mov_b32 s3, 0
	v_lshl_add_u64 v[140:141], s[14:15], 0, v[192:193]
	v_lshl_add_u64 v[142:143], s[16:17], 0, v[192:193]
	v_mul_u32_u24_e32 v173, 0xc0, v215
	v_lshlrev_b32_e32 v174, 1, v216
	v_mov_b32_e32 v52, v0
	v_mov_b32_e32 v53, v0
	v_mov_b32_e32 v54, v0
	v_mov_b32_e32 v55, v0
	v_mov_b32_e32 v56, v0
	v_mov_b32_e32 v57, v0
	v_mov_b32_e32 v58, v0
	v_mov_b32_e32 v59, v0
	v_mov_b32_e32 v60, v0
	v_mov_b32_e32 v61, v0
	v_mov_b32_e32 v62, v0
	v_mov_b32_e32 v63, v0
	v_mov_b32_e32 v64, v0
	v_mov_b32_e32 v65, v0
	v_mov_b32_e32 v66, v0
	v_mov_b32_e32 v67, v0
	v_mov_b32_e32 v68, v0
	v_mov_b32_e32 v69, v0
	v_mov_b32_e32 v70, v0
	v_mov_b32_e32 v71, v0
	v_mov_b32_e32 v72, v0
	v_mov_b32_e32 v73, v0
	v_mov_b32_e32 v74, v0
	v_mov_b32_e32 v75, v0
	v_mov_b32_e32 v76, v0
	v_mov_b32_e32 v77, v0
	v_mov_b32_e32 v78, v0
	v_mov_b32_e32 v79, v0
	v_mov_b32_e32 v144, v0
	v_mov_b32_e32 v145, v0
	s_waitcnt vmcnt(7)
	v_and_b32_e32 v36, 0xffff0000, v20
	v_lshlrev_b32_e32 v1, 16, v20
	v_lshlrev_b32_e32 v37, 16, v21
	s_waitcnt vmcnt(4)
	ds_write_b128 v139, v[32:35] offset:43104
	v_and_b32_e32 v15, 0xffff0000, v34
	v_lshlrev_b32_e32 v14, 16, v34
	v_mul_f32_e32 v34, v36, v36
	v_fmac_f32_e32 v34, v1, v1
	v_and_b32_e32 v38, 0xffff0000, v21
	v_fmac_f32_e32 v34, v37, v37
	v_lshlrev_b32_e32 v39, 16, v22
	v_fmac_f32_e32 v34, v38, v38
	ds_write_b128 v139, v[20:23] offset:43008
	v_and_b32_e32 v22, 0xffff0000, v22
	v_fmac_f32_e32 v34, v39, v39
	v_lshlrev_b32_e32 v40, 16, v23
	v_fmac_f32_e32 v34, v22, v22
	v_and_b32_e32 v23, 0xffff0000, v23
	v_fmac_f32_e32 v34, v40, v40
	v_lshlrev_b32_e32 v41, 16, v24
	v_fmac_f32_e32 v34, v23, v23
	ds_write_b128 v139, v[24:27] offset:43040
	v_and_b32_e32 v24, 0xffff0000, v24
	v_fmac_f32_e32 v34, v41, v41
	v_lshlrev_b32_e32 v42, 16, v25
	v_fmac_f32_e32 v34, v24, v24
	v_and_b32_e32 v25, 0xffff0000, v25
	v_fmac_f32_e32 v34, v42, v42
	v_lshlrev_b32_e32 v43, 16, v26
	v_fmac_f32_e32 v34, v25, v25
	v_and_b32_e32 v26, 0xffff0000, v26
	v_fmac_f32_e32 v34, v43, v43
	v_lshlrev_b32_e32 v44, 16, v27
	v_fmac_f32_e32 v34, v26, v26
	v_and_b32_e32 v27, 0xffff0000, v27
	v_fmac_f32_e32 v34, v44, v44
	v_lshlrev_b32_e32 v45, 16, v28
	v_fmac_f32_e32 v34, v27, v27
	ds_write_b128 v139, v[28:31] offset:43072
	v_and_b32_e32 v28, 0xffff0000, v28
	v_fmac_f32_e32 v34, v45, v45
	v_lshlrev_b32_e32 v46, 16, v29
	v_fmac_f32_e32 v34, v28, v28
	v_and_b32_e32 v29, 0xffff0000, v29
	v_fmac_f32_e32 v34, v46, v46
	v_lshlrev_b32_e32 v47, 16, v30
	v_fmac_f32_e32 v34, v29, v29
	v_and_b32_e32 v30, 0xffff0000, v30
	v_fmac_f32_e32 v34, v47, v47
	v_lshlrev_b32_e32 v48, 16, v31
	v_fmac_f32_e32 v34, v30, v30
	v_and_b32_e32 v31, 0xffff0000, v31
	v_fmac_f32_e32 v34, v48, v48
	v_lshlrev_b32_e32 v49, 16, v32
	v_fmac_f32_e32 v34, v31, v31
	v_and_b32_e32 v32, 0xffff0000, v32
	v_fmac_f32_e32 v34, v49, v49
	v_lshlrev_b32_e32 v50, 16, v33
	v_fmac_f32_e32 v34, v32, v32
	v_and_b32_e32 v33, 0xffff0000, v33
	v_fmac_f32_e32 v34, v50, v50
	v_pk_mul_f32 v[14:15], v[14:15], v[14:15]
	v_fmac_f32_e32 v34, v33, v33
	v_and_b32_e32 v21, 0xffff0000, v35
	v_lshlrev_b32_e32 v20, 16, v35
	v_add_f32_e32 v14, v14, v34
	v_pk_mul_f32 v[20:21], v[20:21], v[20:21]
	v_add_f32_e32 v14, v15, v14
	v_add_f32_e32 v14, v20, v14
	v_add_f32_e32 v14, v21, v14
	v_mov_b32_e32 v15, v14
	s_nop 1
	v_permlane32_swap_b32_e32 v14, v15
	v_add_f32_e32 v14, v14, v15
	v_mul_f32_e32 v15, 0x4f800000, v14
	v_cmp_gt_f32_e32 vcc, s2, v14
	s_waitcnt vmcnt(3)
; __device__ __forceinline__ float bf2f(unsigned short b) { return __uint_as_float((unsigned)b << 16); }
; __device__ __forceinline__ float sum_x32(float v) { auto rr = __builtin_amdgcn_permlane32_swap(__float_as_uint(v), __float_as_uint(v), false, false); return __uint_as_float(rr[0]) + __uint_as_float(rr[1]); }
; __device__ __forceinline__ void attn_pass_A2(const int tid, unsigned char* smem, const bf16_t* Q0w, int qpitch, const bf16_t* Kb, int kpitch, const bf16_t* Vb, int vpitch,
;                                              int b, int ntiles, float kmax, f32x16 (&o)[2][2], float (&linv)[2]) {
;     ...
;         const bf16_t* qp = Q0w + (size_t)(32 * qb + r32) * qpitch + 8 * hi; float ssq = 0.f;
; #pragma unroll
;         for (int ds = 0; ds < 4; ++ds) { const bf16x8 qv = *(const bf16x8*)(qp + 16 * ds); *(bf16x8*)(qs + qb * 32 * KP + ds * 32) = qv;
; #pragma unroll
;             for (int j = 0; j < 8; ++j) { const float f = bf2f((unsigned short)qv[j]); ssq += f * f; } }
;         nshift[qb] = -sqrtf(sum_x32(ssq)) * kmax;
; #pragma unroll
;         for (int d0 = 0; d0 < 2; ++d0)
; #pragma unroll
;             for (int r = 0; r < 16; ++r) o[qb][d0][r] = 0.f;
;     }
;     const int krow = tid >> 3, kch = tid & 7;
;     u32x4 kreg, vreg;
;     auto gload = [&](int kt) {
;         const size_t rb = kt < 4 ? (size_t)(NLAT + 256 * b + 64 * kt) : (size_t)(SEQ * b + 64 * (kt - 4));
;         kreg = *(const u32x4*)(Kb + (rb + krow) * kpitch + 8 * kch); vreg = *(const u32x4*)(Vb + (rb + krow) * vpitch + 8 * kch);
;     };
;     auto lwrite = [&](int buf) { unsigned char* Ks = smem + buf * BUF; *(u32x4*)(Ks + krow * KP + 16 * kch) = kreg; *(u32x4*)(Ks + KBYTES + krow * VP + 16 * kch) = vreg; };
;     gload(0); lwrite(0); __syncthreads();
	ds_write_b128 v139, v[16:19] offset:47616
	v_lshlrev_b32_e32 v35, 16, v16
	v_cndmask_b32_e32 v14, v14, v15, vcc
	v_sqrt_f32_e32 v15, v14
	v_and_b32_e32 v16, 0xffff0000, v16
	v_mul_f32_e32 v1, v16, v16
	v_lshlrev_b32_e32 v36, 16, v17
	v_fmac_f32_e32 v1, v35, v35
	v_and_b32_e32 v17, 0xffff0000, v17
	v_fmac_f32_e32 v1, v36, v36
	v_add_u32_e32 v16, -1, v15
	v_fmac_f32_e32 v1, v17, v17
	v_add_u32_e32 v17, 1, v15
	v_fma_f32 v20, -v16, v15, v14
	v_fma_f32 v21, -v17, v15, v14
	v_cmp_ge_f32_e64 s[0:1], 0, v20
	v_lshlrev_b32_e32 v51, 16, v18
	v_fmac_f32_e32 v1, v51, v51
	v_cndmask_b32_e64 v15, v15, v16, s[0:1]
	v_cmp_lt_f32_e64 s[0:1], 0, v21
	v_mov_b32_e32 v32, v0
	v_mov_b32_e32 v33, v0
	v_cndmask_b32_e64 v15, v15, v17, s[0:1]
	v_mul_f32_e32 v16, 0x37800000, v15
	v_cndmask_b32_e32 v15, v15, v16, vcc
	v_cmp_class_f32_e32 vcc, v14, v227
	s_lshl_b32 s0, s10, 8
	s_add_i32 s0, s0, 0x8000
	v_cndmask_b32_e32 v14, v15, v14, vcc
	v_mul_f32_e64 v16, v214, -v14
	v_and_b32_e32 v14, 0xffff0000, v18
	v_fmac_f32_e32 v1, v14, v14
	v_lshlrev_b32_e32 v14, 16, v19
	s_ashr_i32 s1, s0, 31
	v_fmac_f32_e32 v1, v14, v14
	v_lshl_add_u64 v[14:15], s[0:1], 0, v[136:137]
	v_lshlrev_b64 v[14:15], 8, v[14:15]
	v_and_b32_e32 v17, 0xffff0000, v19
	v_lshl_add_u64 v[18:19], s[14:15], 0, v[14:15]
	v_lshl_add_u64 v[18:19], v[18:19], 0, v[192:193]
	v_lshl_add_u64 v[14:15], s[16:17], 0, v[14:15]
	global_load_dwordx4 v[128:131], v[18:19], off
	v_lshl_add_u64 v[14:15], v[14:15], 0, v[192:193]
	global_load_dwordx4 v[132:135], v[14:15], off
	v_fmac_f32_e32 v1, v17, v17
	s_waitcnt vmcnt(4)
	v_lshlrev_b32_e32 v14, 16, v2
	v_fmac_f32_e32 v1, v14, v14
	v_and_b32_e32 v14, 0xffff0000, v2
	v_fmac_f32_e32 v1, v14, v14
	v_lshlrev_b32_e32 v14, 16, v3
	v_fmac_f32_e32 v1, v14, v14
	v_and_b32_e32 v14, 0xffff0000, v3
	v_fmac_f32_e32 v1, v14, v14
	v_lshlrev_b32_e32 v14, 16, v4
	v_fmac_f32_e32 v1, v14, v14
	v_and_b32_e32 v14, 0xffff0000, v4
	v_fmac_f32_e32 v1, v14, v14
	v_lshlrev_b32_e32 v14, 16, v5
	v_fmac_f32_e32 v1, v14, v14
	v_and_b32_e32 v14, 0xffff0000, v5
	v_fmac_f32_e32 v1, v14, v14
	s_waitcnt vmcnt(3)
	v_lshlrev_b32_e32 v14, 16, v6
	v_fmac_f32_e32 v1, v14, v14
	v_and_b32_e32 v14, 0xffff0000, v6
	v_fmac_f32_e32 v1, v14, v14
	v_lshlrev_b32_e32 v14, 16, v7
	v_fmac_f32_e32 v1, v14, v14
	v_and_b32_e32 v14, 0xffff0000, v7
	v_fmac_f32_e32 v1, v14, v14
	v_lshlrev_b32_e32 v14, 16, v8
	v_fmac_f32_e32 v1, v14, v14
	v_and_b32_e32 v14, 0xffff0000, v8
	v_fmac_f32_e32 v1, v14, v14
	v_lshlrev_b32_e32 v14, 16, v9
	v_fmac_f32_e32 v1, v14, v14
	v_and_b32_e32 v14, 0xffff0000, v9
	v_fmac_f32_e32 v1, v14, v14
	s_waitcnt vmcnt(2)
	v_lshlrev_b32_e32 v14, 16, v10
	v_fmac_f32_e32 v1, v14, v14
	v_and_b32_e32 v14, 0xffff0000, v10
	v_fmac_f32_e32 v1, v14, v14
	v_lshlrev_b32_e32 v14, 16, v11
	v_fmac_f32_e32 v1, v14, v14
	v_and_b32_e32 v14, 0xffff0000, v11
	v_fmac_f32_e32 v1, v14, v14
	v_and_b32_e32 v15, 0xffff0000, v12
	v_lshlrev_b32_e32 v14, 16, v12
	v_pk_mul_f32 v[14:15], v[14:15], v[14:15]
	ds_write_b128 v139, v[2:5] offset:47648
	ds_write_b128 v139, v[6:9] offset:47680
	ds_write_b128 v139, v[10:13] offset:47712
	v_add_f32_e32 v1, v14, v1
	v_add_f32_e32 v1, v15, v1
	v_and_b32_e32 v15, 0xffff0000, v13
	v_lshlrev_b32_e32 v14, 16, v13
	v_pk_mul_f32 v[14:15], v[14:15], v[14:15]
	v_mov_b32_e32 v17, v16
	v_add_f32_e32 v1, v14, v1
	v_add_f32_e32 v1, v15, v1
	v_mov_b32_e32 v14, v1
	s_nop 1
	v_permlane32_swap_b32_e32 v1, v14
	v_add_f32_e32 v1, v1, v14
	v_mul_f32_e32 v14, 0x4f800000, v1
	v_cmp_gt_f32_e32 vcc, s2, v1
	v_mov_b32_e32 v18, v16
	v_mov_b32_e32 v19, v16
	v_cndmask_b32_e32 v1, v1, v14, vcc
	v_sqrt_f32_e32 v14, v1
	v_mov_b32_e32 v20, v16
	v_mov_b32_e32 v21, v16
	v_mov_b32_e32 v22, v16
	v_add_u32_e32 v2, -1, v14
	v_fma_f32 v3, -v2, v14, v1
	v_cmp_ge_f32_e64 s[0:1], 0, v3
	v_add_u32_e32 v3, 1, v14
	v_fma_f32 v4, -v3, v14, v1
	v_cndmask_b32_e64 v2, v14, v2, s[0:1]
	v_cmp_lt_f32_e64 s[0:1], 0, v4
	v_mov_b32_e32 v23, v16
	v_mov_b32_e32 v24, v16
	v_cndmask_b32_e64 v2, v2, v3, s[0:1]
	v_mul_f32_e32 v3, 0x37800000, v2
	v_cndmask_b32_e32 v2, v2, v3, vcc
	v_cmp_class_f32_e32 vcc, v1, v227
	s_movk_i32 s0, 0xc0
	v_mul_lo_u32 v172, v136, s0
	v_cndmask_b32_e32 v1, v2, v1, vcc
	v_add3_u32 v2, 0, v212, v192
	v_mul_f32_e64 v80, v214, -v1
	s_waitcnt vmcnt(1)
	ds_write_b128 v2, v[128:131]
	v_mad_u64_u32 v[2:3], s[0:1], v136, 48, v[2:3]
	s_waitcnt vmcnt(0)
	ds_write_b128 v2, v[132:135] offset:9216
	v_mov_b32_e32 v25, v16
	v_mov_b32_e32 v26, v16
	v_mov_b32_e32 v27, v16
	v_mov_b32_e32 v28, v16
	v_mov_b32_e32 v29, v16
	v_mov_b32_e32 v30, v16
	v_mov_b32_e32 v31, v16
	v_mov_b32_e32 v81, v80
	v_mov_b32_e32 v82, v80
	v_mov_b32_e32 v83, v80
	v_mov_b32_e32 v84, v80
	v_mov_b32_e32 v85, v80
	v_mov_b32_e32 v86, v80
	v_mov_b32_e32 v87, v80
	v_mov_b32_e32 v88, v80
	v_mov_b32_e32 v89, v80
	v_mov_b32_e32 v90, v80
	v_mov_b32_e32 v91, v80
	v_mov_b32_e32 v92, v80
	v_mov_b32_e32 v93, v80
	v_mov_b32_e32 v94, v80
	v_mov_b32_e32 v95, v80
	s_mov_b32 s2, 64
	v_mov_b32_e32 v1, v0
	v_mov_b32_e32 v2, v0
	v_mov_b32_e32 v3, v0
	v_mov_b32_e32 v4, v0
	v_mov_b32_e32 v5, v0
	v_mov_b32_e32 v6, v0
	v_mov_b32_e32 v7, v0
	v_mov_b32_e32 v8, v0
	v_mov_b32_e32 v9, v0
	v_mov_b32_e32 v10, v0
	v_mov_b32_e32 v11, v0
	v_mov_b32_e32 v12, v0
	v_mov_b32_e32 v13, v0
	v_mov_b32_e32 v14, v0
	v_mov_b32_e32 v15, v0
	v_mov_b32_e32 v34, v0
	v_mov_b32_e32 v35, v0
	v_mov_b32_e32 v36, v0
	v_mov_b32_e32 v37, v0
	v_mov_b32_e32 v38, v0
	v_mov_b32_e32 v39, v0
	v_mov_b32_e32 v40, v0
	v_mov_b32_e32 v41, v0
	v_mov_b32_e32 v42, v0
	v_mov_b32_e32 v43, v0
	v_mov_b32_e32 v44, v0
	v_mov_b32_e32 v45, v0
	v_mov_b32_e32 v46, v0
	v_mov_b32_e32 v47, v0
	v_mov_b32_e32 v48, v0
	v_mov_b32_e32 v49, v0
	v_mov_b32_e32 v50, v0
	v_mov_b32_e32 v51, v0
	s_waitcnt lgkmcnt(0)
	s_barrier
	s_cmp_ge_u32 s27, 0x100
	s_cbranch_scc0 .La_prio_skip
	s_setprio 1
; __device__ __forceinline__ void attn_pass_A2(const int tid, unsigned char* smem, const bf16_t* Q0w, int qpitch, const bf16_t* Kb, int kpitch, const bf16_t* Vb, int vpitch,
;                                              int b, int ntiles, float kmax, f32x16 (&o)[2][2], float (&linv)[2]) {
;     ...
;     gload(0); lwrite(0); __syncthreads();
;     const int nhalf = (lane >> 4) & 1, q4 = (lane & 15) >> 2, p4 = lane & 3;
;     for (int kt = 0; kt < ntiles; ++kt) {
;         if (kt + 1 < ntiles) gload(kt + 1);
;         const unsigned char* Ks = smem + (kt & 1) * BUF; const unsigned char* Vs = Ks + KBYTES;
;         const unsigned char* kp = Ks + r32 * KP + hi * 16;
;         const unsigned char* vp = Vs + (4 * hi + q4) * VP + (16 * nhalf + 4 * p4) * 2;
; #pragma unroll
;         for (int kb = 0; kb < 2; ++kb) {
;             bf16x8 pf[2][2];
;             {
;                 f32x16 s0, s1;
; #pragma unroll
;                 for (int r = 0; r < 16; ++r) { s0[r] = nshift[0]; s1[r] = nshift[1]; }
; #pragma unroll
;                 for (int ds = 0; ds < 4; ++ds) {
;                     const bf16x8 kf = *(const bf16x8*)(kp + kb * 32 * KP + ds * 32);
;                     const bf16x8 q0 = *(const bf16x8*)(qs + ds * 32), q1 = *(const bf16x8*)(qs + 32 * KP + ds * 32);
;                     s0 = __builtin_amdgcn_mfma_f32_32x32x16_bf16(kf, q0, s0, 0, 0, 0);
;                     s1 = __builtin_amdgcn_mfma_f32_32x32x16_bf16(kf, q1, s1, 0, 0, 0);
;                 }
;                 float l0 = 0.f, l1 = 0.f;
; #pragma unroll
;                 for (int r = 0; r < 16; ++r) { s0[r] = __builtin_amdgcn_exp2f(s0[r]); l0 += s0[r]; }
; #pragma unroll
;                 for (int r = 0; r < 16; ++r) { s1[r] = __builtin_amdgcn_exp2f(s1[r]); l1 += s1[r]; }
;                 lsum[0] += l0; lsum[1] += l1;
; #pragma unroll
;                 for (int j = 0; j < 2; ++j) {
;                     u32x4 w0, w1;
;                     w0.x = cvt_pk_bf16(s0[8 * j + 0], s0[8 * j + 1]); w0.y = cvt_pk_bf16(s0[8 * j + 2], s0[8 * j + 3]); w0.z = cvt_pk_bf16(s0[8 * j + 4], s0[8 * j + 5]); w0.w = cvt_pk_bf16(s0[8 * j + 6], s0[8 * j + 7]);
;                     w1.x = cvt_pk_bf16(s1[8 * j + 0], s1[8 * j + 1]); w1.y = cvt_pk_bf16(s1[8 * j + 2], s1[8 * j + 3]); w1.z = cvt_pk_bf16(s1[8 * j + 4], s1[8 * j + 5]); w1.w = cvt_pk_bf16(s1[8 * j + 6], s1[8 * j + 7]);
.La_prio_skip:
	s_mov_b64 s[66:67], s[14:15]
	s_mov_b64 s[68:69], s[16:17]
	s_lshl_b32 s2, s10, 8
	s_add_i32 s65, s2, 0x8000
	s_lshl_b32 s2, s10, 13
	s_add_i32 s32, s2, 0xffffff00
	s_lshr_b32 s56, s27, 6
	s_lshl_b32 s56, s56, 10
	v_and_b32_e32 v132, 7, v197
	v_bfe_u32 v133, v136, 1, 3
	v_xor_b32_e32 v133, v133, v132
	v_lshlrev_b32_e32 v133, 4, v133
	v_lshl_add_u32 v236, v136, 8, v133
	v_bfe_u32 v134, v136, 1, 1
	v_lshlrev_b32_e32 v134, 2, v134
	v_xor_b32_e32 v134, v134, v132
	v_lshlrev_b32_e32 v134, 4, v134
	v_lshl_add_u32 v234, v136, 8, v134
	s_mov_b32 s59, 0
	s_waitcnt vmcnt(0)
	s_add_i32 s70, s59, 0
	s_cmp_lt_u32 s70, 4
	s_cselect_b32 s2, s65, s32
	s_lshl_b32 s3, s70, 6
	s_add_i32 s2, s2, s3
	s_lshl_b32 s2, s2, 8
	s_add_u32 s60, s66, s2
	s_addc_u32 s61, s67, 0
	s_add_u32 s62, s68, s2
	s_addc_u32 s63, s69, 0
	s_mov_b32 m0, s56
	s_nop 0
	global_load_lds_dwordx4 v236, s[60:61]
	s_add_i32 m0, s56, 0x2000
	s_nop 0
	global_load_lds_dwordx4 v234, s[62:63]
	s_add_i32 s70, s59, 1
	s_cmp_lt_u32 s70, 4
	s_cselect_b32 s2, s65, s32
	s_lshl_b32 s3, s70, 6
	s_add_i32 s2, s2, s3
	s_lshl_b32 s2, s2, 8
	s_add_u32 s60, s66, s2
	s_addc_u32 s61, s67, 0
	s_add_u32 s62, s68, s2
	s_addc_u32 s63, s69, 0
	s_add_i32 m0, s56, 0x4000
	s_nop 0
	global_load_lds_dwordx4 v236, s[60:61]
	s_add_i32 m0, s56, 0x6000
	s_nop 0
	global_load_lds_dwordx4 v234, s[62:63]
	v_min_f32_e32 v16, v16, v80
	v_mov_b32_e32 v17, v16
	v_mov_b32_e32 v18, v16
	v_mov_b32_e32 v19, v16
	v_mov_b32_e32 v20, v16
	v_mov_b32_e32 v21, v16
	v_mov_b32_e32 v22, v16
	v_mov_b32_e32 v23, v16
	v_mov_b32_e32 v24, v16
	v_mov_b32_e32 v25, v16
	v_mov_b32_e32 v26, v16
	v_mov_b32_e32 v27, v16
	v_mov_b32_e32 v28, v16
	v_mov_b32_e32 v29, v16
	v_mov_b32_e32 v30, v16
	v_mov_b32_e32 v31, v16
	ds_read_b128 v[146:149], v139 offset:43008
	ds_read_b128 v[150:153], v139 offset:43040
	ds_read_b128 v[154:157], v139 offset:43072
	ds_read_b128 v[158:161], v139 offset:43104
	ds_read_b128 v[176:179], v139 offset:47616
	ds_read_b128 v[180:183], v139 offset:47648
	ds_read_b128 v[184:187], v139 offset:47680
	ds_read_b128 v[188:191], v139 offset:47712
	v_bfe_u32 v132, v218, 1, 3
	v_lshrrev_b32_e32 v133, 4, v138
	v_xor_b32_e32 v132, v132, v133
	v_xor_b32_e32 v133, 0, v132
	v_lshlrev_b32_e32 v133, 4, v133
	v_lshl_or_b32 v170, v218, 7, v133
	v_xor_b32_e32 v133, 2, v132
	v_lshlrev_b32_e32 v133, 4, v133
	v_lshl_or_b32 v171, v218, 7, v133
	v_xor_b32_e32 v133, 4, v132
	v_lshlrev_b32_e32 v133, 4, v133
	v_lshl_or_b32 v210, v218, 7, v133
	v_xor_b32_e32 v133, 6, v132
	v_lshlrev_b32_e32 v133, 4, v133
	v_lshl_or_b32 v222, v218, 7, v133
	v_bfe_u32 v134, v215, 1, 1
	v_xor_b32_e32 v135, 0, v134
	v_lshl_add_u32 v135, v135, 6, v174
	v_lshl_add_u32 v223, v215, 7, v135
	v_xor_b32_e32 v135, 1, v134
	v_lshl_add_u32 v135, v135, 6, v174
	v_lshl_add_u32 v224, v215, 7, v135
	s_waitcnt vmcnt(0) lgkmcnt(0)
	s_barrier
	s_add_i32 s70, s59, 2
	s_cmp_lt_u32 s70, 4
	s_cselect_b32 s2, s65, s32
	s_lshl_b32 s3, s70, 6
	s_add_i32 s2, s2, s3
	s_lshl_b32 s2, s2, 8
	s_add_u32 s60, s66, s2
	s_addc_u32 s61, s67, 0
	s_add_u32 s62, s68, s2
	s_addc_u32 s63, s69, 0
	s_add_i32 m0, s56, 0x8000
	s_nop 0
	global_load_lds_dwordx4 v236, s[60:61]
	s_add_i32 m0, s56, 0xa000
	s_nop 0
	global_load_lds_dwordx4 v234, s[62:63]
	ds_read_b128 v[198:201], v170
	ds_read_b128 v[202:205], v171
	ds_read_b128 v[206:209], v210
	ds_read_b128 v[128:131], v222
	s_waitcnt lgkmcnt(3)
	v_mfma_f32_32x32x16_bf16 v[80:95], v[198:201], v[146:149], v[16:31]
	s_waitcnt lgkmcnt(2)
	v_mfma_f32_32x32x16_bf16 v[80:95], v[202:205], v[150:153], v[80:95]
	s_waitcnt lgkmcnt(1)
	v_mfma_f32_32x32x16_bf16 v[80:95], v[206:209], v[154:157], v[80:95]
	s_waitcnt lgkmcnt(0)
	v_mfma_f32_32x32x16_bf16 v[80:95], v[128:131], v[158:161], v[80:95]
	s_nop 7
	s_nop 3
	v_mfma_f32_32x32x16_bf16 v[96:111], v[198:201], v[176:179], v[16:31]
	ds_read_b128 v[198:201], v170 offset:4096
	v_exp_f32_e32 v80, v80
	v_exp_f32_e32 v81, v81
	v_exp_f32_e32 v82, v82
	v_add_f32_e32 v144, v144, v80
	v_exp_f32_e32 v83, v83
	v_add_f32_e32 v144, v144, v81
	v_cvt_pk_bf16_f32 v112, v80, v81
	v_exp_f32_e32 v84, v84
	v_add_f32_e32 v144, v144, v82
	v_exp_f32_e32 v85, v85
	v_add_f32_e32 v144, v144, v83
	v_cvt_pk_bf16_f32 v113, v82, v83
	v_exp_f32_e32 v86, v86
	v_mfma_f32_32x32x16_bf16 v[96:111], v[202:205], v[180:183], v[96:111]
	ds_read_b128 v[202:205], v171 offset:4096
	v_add_f32_e32 v144, v144, v84
	v_exp_f32_e32 v87, v87
	v_add_f32_e32 v144, v144, v85
	v_cvt_pk_bf16_f32 v114, v84, v85
	v_exp_f32_e32 v88, v88
	v_add_f32_e32 v144, v144, v86
	v_exp_f32_e32 v89, v89
	v_add_f32_e32 v144, v144, v87
	v_cvt_pk_bf16_f32 v115, v86, v87
	v_exp_f32_e32 v90, v90
	v_add_f32_e32 v144, v144, v88
	v_exp_f32_e32 v91, v91
	v_add_f32_e32 v144, v144, v89
	v_mfma_f32_32x32x16_bf16 v[96:111], v[206:209], v[184:187], v[96:111]
	ds_read_b128 v[206:209], v210 offset:4096
	v_cvt_pk_bf16_f32 v116, v88, v89
	v_exp_f32_e32 v92, v92
	v_add_f32_e32 v144, v144, v90
	v_exp_f32_e32 v93, v93
	v_add_f32_e32 v144, v144, v91
	v_cvt_pk_bf16_f32 v117, v90, v91
	v_exp_f32_e32 v94, v94
	v_add_f32_e32 v144, v144, v92
	v_exp_f32_e32 v95, v95
	v_add_f32_e32 v144, v144, v93
	v_cvt_pk_bf16_f32 v118, v92, v93
	v_add_f32_e32 v144, v144, v94
	v_add_f32_e32 v144, v144, v95
	v_cvt_pk_bf16_f32 v119, v94, v95
	v_mfma_f32_32x32x16_bf16 v[96:111], v[128:131], v[188:191], v[96:111]
	ds_read_b128 v[128:131], v222 offset:4096
	ds_read_b64_tr_b16 v[162:163], v223 offset:8192
	ds_read_b64_tr_b16 v[164:165], v223 offset:9216
	ds_read_b64_tr_b16 v[166:167], v224 offset:8192
	ds_read_b64_tr_b16 v[168:169], v224 offset:9216
	ds_read_b64_tr_b16 v[214:215], v223 offset:10240
	ds_read_b64_tr_b16 v[216:217], v223 offset:11264
	ds_read_b64_tr_b16 v[218:219], v224 offset:10240
	ds_read_b64_tr_b16 v[220:221], v224 offset:11264
	s_waitcnt lgkmcnt(8)
	s_nop 3
	s_add_i32 s71, s25, -7
	s_cmp_lt_i32 s59, s71
	s_cbranch_scc0 .Laattn_tail

; __device__ __forceinline__ void attn_pass_A2(const int tid, unsigned char* smem, const bf16_t* Q0w, int qpitch, const bf16_t* Kb, int kpitch, const bf16_t* Vb, int vpitch,
;                                              int b, int ntiles, float kmax, f32x16 (&o)[2][2], float (&linv)[2]) {
;     ...
;     for (int kt = 0; kt < ntiles; ++kt) {
;         if (kt + 1 < ntiles) gload(kt + 1);
;         const unsigned char* Ks = smem + (kt & 1) * BUF; const unsigned char* Vs = Ks + KBYTES;
;         const unsigned char* kp = Ks + r32 * KP + hi * 16;
;         const unsigned char* vp = Vs + (4 * hi + q4) * VP + (16 * nhalf + 4 * p4) * 2;
; #pragma unroll
;         for (int kb = 0; kb < 2; ++kb) {
;             bf16x8 pf[2][2];
;             {
;                 f32x16 s0, s1;
; #pragma unroll
;                 for (int r = 0; r < 16; ++r) { s0[r] = nshift[0]; s1[r] = nshift[1]; }
; #pragma unroll
;                 for (int ds = 0; ds < 4; ++ds) {
;                     const bf16x8 kf = *(const bf16x8*)(kp + kb * 32 * KP + ds * 32);
;                     const bf16x8 q0 = *(const bf16x8*)(qs + ds * 32), q1 = *(const bf16x8*)(qs + 32 * KP + ds * 32);
;                     s0 = __builtin_amdgcn_mfma_f32_32x32x16_bf16(kf, q0, s0, 0, 0, 0);
;                     s1 = __builtin_amdgcn_mfma_f32_32x32x16_bf16(kf, q1, s1, 0, 0, 0);
;                 }
;                 float l0 = 0.f, l1 = 0.f;
; #pragma unroll
;                 for (int r = 0; r < 16; ++r) { s0[r] = __builtin_amdgcn_exp2f(s0[r]); l0 += s0[r]; }
; #pragma unroll
;                 for (int r = 0; r < 16; ++r) { s1[r] = __builtin_amdgcn_exp2f(s1[r]); l1 += s1[r]; }
;                 lsum[0] += l0; lsum[1] += l1;
; #pragma unroll
;                 for (int j = 0; j < 2; ++j) {
;                     u32x4 w0, w1;
;                     w0.x = cvt_pk_bf16(s0[8 * j + 0], s0[8 * j + 1]); w0.y = cvt_pk_bf16(s0[8 * j + 2], s0[8 * j + 3]); w0.z = cvt_pk_bf16(s0[8 * j + 4], s0[8 * j + 5]); w0.w = cvt_pk_bf16(s0[8 * j + 6], s0[8 * j + 7]);
;                     w1.x = cvt_pk_bf16(s1[8 * j + 0], s1[8 * j + 1]); w1.y = cvt_pk_bf16(s1[8 * j + 2], s1[8 * j + 3]); w1.z = cvt_pk_bf16(s1[8 * j + 4], s1[8 * j + 5]); w1.w = cvt_pk_bf16(s1[8 * j + 6], s1[8 * j + 7]);
;                     pf[0][j] = __builtin_bit_cast(bf16x8, w0); pf[1][j] = __builtin_bit_cast(bf16x8, w1);
;                 }
;             }
.Laattn_tail:
	v_mfma_f32_32x32x16_bf16 v[80:95], v[198:201], v[146:149], v[16:31]
	v_exp_f32_e32 v96, v96
	v_exp_f32_e32 v97, v97
	v_exp_f32_e32 v98, v98
	v_add_f32_e32 v145, v145, v96
	v_exp_f32_e32 v99, v99
	v_mfma_f32_32x32x16_bf16 v[80:95], v[202:205], v[150:153], v[80:95]
	s_add_i32 s70, s59, 3
	s_cmp_lt_u32 s70, 4
	s_cselect_b32 s2, s65, s32
	s_lshl_b32 s3, s70, 6
	s_add_i32 s2, s2, s3
	s_lshl_b32 s2, s2, 8
	s_add_u32 s60, s66, s2
	s_addc_u32 s61, s67, 0
	s_add_u32 s62, s68, s2
	s_addc_u32 s63, s69, 0
	v_add_f32_e32 v145, v145, v97
	v_cvt_pk_bf16_f32 v120, v96, v97
	v_exp_f32_e32 v100, v100
	v_add_f32_e32 v145, v145, v98
	v_exp_f32_e32 v101, v101
	v_mfma_f32_32x32x16_bf16 v[80:95], v[206:209], v[154:157], v[80:95]
	v_add_f32_e32 v145, v145, v99
	v_cvt_pk_bf16_f32 v121, v98, v99
	v_exp_f32_e32 v102, v102
	v_add_f32_e32 v145, v145, v100
	v_exp_f32_e32 v103, v103
	v_add_f32_e32 v145, v145, v101
	v_mfma_f32_32x32x16_bf16 v[80:95], v[128:131], v[158:161], v[80:95]
	s_add_i32 m0, s56, 0xc000
	s_nop 0
	global_load_lds_dwordx4 v236, s[60:61]
	v_cvt_pk_bf16_f32 v122, v100, v101
	v_exp_f32_e32 v104, v104
	v_add_f32_e32 v145, v145, v102
	v_exp_f32_e32 v105, v105
	v_add_f32_e32 v145, v145, v103
	v_cvt_pk_bf16_f32 v123, v102, v103
	s_waitcnt lgkmcnt(6)
	v_mfma_f32_32x32x16_bf16 v[64:79], v[162:165], v[112:115], v[64:79]
	v_exp_f32_e32 v106, v106
	v_add_f32_e32 v145, v145, v104
	v_exp_f32_e32 v107, v107
	v_add_f32_e32 v145, v145, v105
	v_cvt_pk_bf16_f32 v124, v104, v105
	v_exp_f32_e32 v108, v108
	s_waitcnt lgkmcnt(4)
	v_mfma_f32_32x32x16_bf16 v[48:63], v[166:169], v[112:115], v[48:63]
	s_add_i32 m0, s56, 0xe000
	s_nop 0
	global_load_lds_dwordx4 v234, s[62:63]
	v_add_f32_e32 v145, v145, v106
	v_exp_f32_e32 v109, v109
	v_add_f32_e32 v145, v145, v107
	v_cvt_pk_bf16_f32 v125, v106, v107
	v_exp_f32_e32 v110, v110
	s_waitcnt lgkmcnt(2)
	v_mfma_f32_32x32x16_bf16 v[64:79], v[214:217], v[116:119], v[64:79]
	v_add_f32_e32 v145, v145, v108
	v_exp_f32_e32 v111, v111
	v_add_f32_e32 v145, v145, v109
	v_cvt_pk_bf16_f32 v126, v108, v109
	v_add_f32_e32 v145, v145, v110
	v_add_f32_e32 v145, v145, v111
	v_cvt_pk_bf16_f32 v127, v110, v111
	s_waitcnt lgkmcnt(0)
	v_mfma_f32_32x32x16_bf16 v[48:63], v[218:221], v[116:119], v[48:63]
	v_mfma_f32_32x32x16_bf16 v[96:111], v[198:201], v[176:179], v[16:31]
	ds_read_b128 v[198:201], v170 offset:16384
	v_exp_f32_e32 v80, v80
	v_exp_f32_e32 v81, v81
	v_exp_f32_e32 v82, v82
	v_add_f32_e32 v144, v144, v80
	v_exp_f32_e32 v83, v83
	v_mfma_f32_32x32x16_bf16 v[96:111], v[202:205], v[180:183], v[96:111]
	ds_read_b128 v[202:205], v171 offset:16384
	v_add_f32_e32 v144, v144, v81
	v_cvt_pk_bf16_f32 v112, v80, v81
	v_exp_f32_e32 v84, v84
	v_add_f32_e32 v144, v144, v82
	v_exp_f32_e32 v85, v85
	v_mfma_f32_32x32x16_bf16 v[96:111], v[206:209], v[184:187], v[96:111]
	ds_read_b128 v[206:209], v210 offset:16384
	v_add_f32_e32 v144, v144, v83
	v_cvt_pk_bf16_f32 v113, v82, v83
	v_exp_f32_e32 v86, v86
	v_add_f32_e32 v144, v144, v84
	v_exp_f32_e32 v87, v87
	v_add_f32_e32 v144, v144, v85
	v_mfma_f32_32x32x16_bf16 v[96:111], v[128:131], v[188:191], v[96:111]
	ds_read_b128 v[128:131], v222 offset:16384
	v_cvt_pk_bf16_f32 v114, v84, v85
	v_exp_f32_e32 v88, v88
	v_add_f32_e32 v144, v144, v86
	v_exp_f32_e32 v89, v89
	v_add_f32_e32 v144, v144, v87
	v_cvt_pk_bf16_f32 v115, v86, v87
	v_mfma_f32_32x32x16_bf16 v[32:47], v[162:165], v[120:123], v[32:47]
	ds_read_b64_tr_b16 v[162:163], v223 offset:12288
	ds_read_b64_tr_b16 v[164:165], v223 offset:13312
	v_exp_f32_e32 v90, v90
	v_add_f32_e32 v144, v144, v88
	v_exp_f32_e32 v91, v91
	v_add_f32_e32 v144, v144, v89
	v_cvt_pk_bf16_f32 v116, v88, v89
	v_exp_f32_e32 v92, v92
	v_mfma_f32_32x32x16_bf16 v[0:15], v[166:169], v[120:123], v[0:15]
	ds_read_b64_tr_b16 v[166:167], v224 offset:12288
	ds_read_b64_tr_b16 v[168:169], v224 offset:13312
	v_add_f32_e32 v144, v144, v90
	v_exp_f32_e32 v93, v93
	v_add_f32_e32 v144, v144, v91
	v_cvt_pk_bf16_f32 v117, v90, v91
	v_exp_f32_e32 v94, v94
	v_mfma_f32_32x32x16_bf16 v[32:47], v[214:217], v[124:127], v[32:47]
	ds_read_b64_tr_b16 v[214:215], v223 offset:14336
	ds_read_b64_tr_b16 v[216:217], v223 offset:15360
	v_add_f32_e32 v144, v144, v92
	v_exp_f32_e32 v95, v95
	v_add_f32_e32 v144, v144, v93
	v_cvt_pk_bf16_f32 v118, v92, v93
	v_add_f32_e32 v144, v144, v94
	v_add_f32_e32 v144, v144, v95
	v_cvt_pk_bf16_f32 v119, v94, v95
	v_mfma_f32_32x32x16_bf16 v[0:15], v[218:221], v[124:127], v[0:15]
	ds_read_b64_tr_b16 v[218:219], v224 offset:14336
	ds_read_b64_tr_b16 v[220:221], v224 offset:15360
	s_waitcnt lgkmcnt(11)
	v_mfma_f32_32x32x16_bf16 v[80:95], v[198:201], v[146:149], v[16:31]
	v_exp_f32_e32 v96, v96
	v_exp_f32_e32 v97, v97
	v_exp_f32_e32 v98, v98
	v_add_f32_e32 v145, v145, v96
	v_exp_f32_e32 v99, v99
	s_waitcnt lgkmcnt(10)
	v_mfma_f32_32x32x16_bf16 v[80:95], v[202:205], v[150:153], v[80:95]
	v_add_f32_e32 v145, v145, v97
	v_cvt_pk_bf16_f32 v120, v96, v97
	v_exp_f32_e32 v100, v100
	v_add_f32_e32 v145, v145, v98
	v_exp_f32_e32 v101, v101
	s_waitcnt lgkmcnt(9)
	v_mfma_f32_32x32x16_bf16 v[80:95], v[206:209], v[154:157], v[80:95]
	v_add_f32_e32 v145, v145, v99
	v_cvt_pk_bf16_f32 v121, v98, v99
	v_exp_f32_e32 v102, v102
	v_add_f32_e32 v145, v145, v100
	v_exp_f32_e32 v103, v103
	v_add_f32_e32 v145, v145, v101
	s_waitcnt lgkmcnt(8)
	v_mfma_f32_32x32x16_bf16 v[80:95], v[128:131], v[158:161], v[80:95]
	v_cvt_pk_bf16_f32 v122, v100, v101
	v_exp_f32_e32 v104, v104
	v_add_f32_e32 v145, v145, v102
	v_exp_f32_e32 v105, v105
	v_add_f32_e32 v145, v145, v103
	v_cvt_pk_bf16_f32 v123, v102, v103
	s_waitcnt lgkmcnt(6)
; __device__ __forceinline__ void attn_pass_A2(const int tid, unsigned char* smem, const bf16_t* Q0w, int qpitch, const bf16_t* Kb, int kpitch, const bf16_t* Vb, int vpitch,
;                                              int b, int ntiles, float kmax, f32x16 (&o)[2][2], float (&linv)[2]) {
;     ...
;     for (int kt = 0; kt < ntiles; ++kt) {
;         if (kt + 1 < ntiles) gload(kt + 1);
;         const unsigned char* Ks = smem + (kt & 1) * BUF; const unsigned char* Vs = Ks + KBYTES;
;         const unsigned char* kp = Ks + r32 * KP + hi * 16;
;         const unsigned char* vp = Vs + (4 * hi + q4) * VP + (16 * nhalf + 4 * p4) * 2;
; #pragma unroll
;         for (int kb = 0; kb < 2; ++kb) {
;             bf16x8 pf[2][2];
;             {
;                 f32x16 s0, s1;
; #pragma unroll
;                 for (int r = 0; r < 16; ++r) { s0[r] = nshift[0]; s1[r] = nshift[1]; }
; #pragma unroll
;                 for (int ds = 0; ds < 4; ++ds) {
;                     const bf16x8 kf = *(const bf16x8*)(kp + kb * 32 * KP + ds * 32);
;                     const bf16x8 q0 = *(const bf16x8*)(qs + ds * 32), q1 = *(const bf16x8*)(qs + 32 * KP + ds * 32);
;                     s0 = __builtin_amdgcn_mfma_f32_32x32x16_bf16(kf, q0, s0, 0, 0, 0);
;                     s1 = __builtin_amdgcn_mfma_f32_32x32x16_bf16(kf, q1, s1, 0, 0, 0);
;                 }
;                 float l0 = 0.f, l1 = 0.f;
; #pragma unroll
;                 for (int r = 0; r < 16; ++r) { s0[r] = __builtin_amdgcn_exp2f(s0[r]); l0 += s0[r]; }
; #pragma unroll
;                 for (int r = 0; r < 16; ++r) { s1[r] = __builtin_amdgcn_exp2f(s1[r]); l1 += s1[r]; }
;                 lsum[0] += l0; lsum[1] += l1;
; #pragma unroll
;                 for (int j = 0; j < 2; ++j) {
;                     u32x4 w0, w1;
;                     w0.x = cvt_pk_bf16(s0[8 * j + 0], s0[8 * j + 1]); w0.y = cvt_pk_bf16(s0[8 * j + 2], s0[8 * j + 3]); w0.z = cvt_pk_bf16(s0[8 * j + 4], s0[8 * j + 5]); w0.w = cvt_pk_bf16(s0[8 * j + 6], s0[8 * j + 7]);
;                     w1.x = cvt_pk_bf16(s1[8 * j + 0], s1[8 * j + 1]); w1.y = cvt_pk_bf16(s1[8 * j + 2], s1[8 * j + 3]); w1.z = cvt_pk_bf16(s1[8 * j + 4], s1[8 * j + 5]); w1.w = cvt_pk_bf16(s1[8 * j + 6], s1[8 * j + 7]);
;                     pf[0][j] = __builtin_bit_cast(bf16x8, w0); pf[1][j] = __builtin_bit_cast(bf16x8, w1);
;                 }
;             }
	v_mfma_f32_32x32x16_bf16 v[64:79], v[162:165], v[112:115], v[64:79]
	v_exp_f32_e32 v106, v106
	v_add_f32_e32 v145, v145, v104
	v_exp_f32_e32 v107, v107
	v_add_f32_e32 v145, v145, v105
	v_cvt_pk_bf16_f32 v124, v104, v105
	v_exp_f32_e32 v108, v108
	s_waitcnt lgkmcnt(4)
	v_mfma_f32_32x32x16_bf16 v[48:63], v[166:169], v[112:115], v[48:63]
	v_add_f32_e32 v145, v145, v106
	v_exp_f32_e32 v109, v109
	v_add_f32_e32 v145, v145, v107
	v_cvt_pk_bf16_f32 v125, v106, v107
	v_exp_f32_e32 v110, v110
	s_waitcnt lgkmcnt(2)
	v_mfma_f32_32x32x16_bf16 v[64:79], v[214:217], v[116:119], v[64:79]
	v_add_f32_e32 v145, v145, v108
	v_exp_f32_e32 v111, v111
	v_add_f32_e32 v145, v145, v109
	v_cvt_pk_bf16_f32 v126, v108, v109
	v_add_f32_e32 v145, v145, v110
	v_add_f32_e32 v145, v145, v111
	v_cvt_pk_bf16_f32 v127, v110, v111
	s_waitcnt lgkmcnt(0)
	v_mfma_f32_32x32x16_bf16 v[48:63], v[218:221], v[116:119], v[48:63]
	v_mfma_f32_32x32x16_bf16 v[96:111], v[198:201], v[176:179], v[16:31]
	ds_read_b128 v[198:201], v170 offset:20480
	v_exp_f32_e32 v80, v80
	v_exp_f32_e32 v81, v81
	v_exp_f32_e32 v82, v82
	v_add_f32_e32 v144, v144, v80
	v_exp_f32_e32 v83, v83
	v_mfma_f32_32x32x16_bf16 v[96:111], v[202:205], v[180:183], v[96:111]
	ds_read_b128 v[202:205], v171 offset:20480
	v_add_f32_e32 v144, v144, v81
	v_cvt_pk_bf16_f32 v112, v80, v81
	v_exp_f32_e32 v84, v84
	v_add_f32_e32 v144, v144, v82
	v_exp_f32_e32 v85, v85
	v_mfma_f32_32x32x16_bf16 v[96:111], v[206:209], v[184:187], v[96:111]
	ds_read_b128 v[206:209], v210 offset:20480
	v_add_f32_e32 v144, v144, v83
	v_cvt_pk_bf16_f32 v113, v82, v83
	v_exp_f32_e32 v86, v86
	v_add_f32_e32 v144, v144, v84
	v_exp_f32_e32 v87, v87
	v_add_f32_e32 v144, v144, v85
	v_mfma_f32_32x32x16_bf16 v[96:111], v[128:131], v[188:191], v[96:111]
	ds_read_b128 v[128:131], v222 offset:20480
	v_cvt_pk_bf16_f32 v114, v84, v85
	v_exp_f32_e32 v88, v88
	v_add_f32_e32 v144, v144, v86
	v_exp_f32_e32 v89, v89
	v_add_f32_e32 v144, v144, v87
	v_cvt_pk_bf16_f32 v115, v86, v87
	v_mfma_f32_32x32x16_bf16 v[32:47], v[162:165], v[120:123], v[32:47]
	ds_read_b64_tr_b16 v[162:163], v223 offset:24576
	ds_read_b64_tr_b16 v[164:165], v223 offset:25600
	v_exp_f32_e32 v90, v90
	v_add_f32_e32 v144, v144, v88
	v_exp_f32_e32 v91, v91
	v_add_f32_e32 v144, v144, v89
	v_cvt_pk_bf16_f32 v116, v88, v89
	v_exp_f32_e32 v92, v92
	v_mfma_f32_32x32x16_bf16 v[0:15], v[166:169], v[120:123], v[0:15]
	ds_read_b64_tr_b16 v[166:167], v224 offset:24576
	ds_read_b64_tr_b16 v[168:169], v224 offset:25600
	s_add_i32 s59, s59, 1
	v_add_f32_e32 v144, v144, v90
	v_exp_f32_e32 v93, v93
	v_add_f32_e32 v144, v144, v91
	v_cvt_pk_bf16_f32 v117, v90, v91
	v_exp_f32_e32 v94, v94
	v_mfma_f32_32x32x16_bf16 v[32:47], v[214:217], v[124:127], v[32:47]
	ds_read_b64_tr_b16 v[214:215], v223 offset:26624
	ds_read_b64_tr_b16 v[216:217], v223 offset:27648
	v_add_f32_e32 v144, v144, v92
	v_exp_f32_e32 v95, v95
	v_add_f32_e32 v144, v144, v93
	v_cvt_pk_bf16_f32 v118, v92, v93
	v_add_f32_e32 v144, v144, v94
	v_add_f32_e32 v144, v144, v95
	v_cvt_pk_bf16_f32 v119, v94, v95
	v_mfma_f32_32x32x16_bf16 v[0:15], v[218:221], v[124:127], v[0:15]
	ds_read_b64_tr_b16 v[218:219], v224 offset:26624
	ds_read_b64_tr_b16 v[220:221], v224 offset:27648
	s_waitcnt vmcnt(2) lgkmcnt(8)
	s_barrier
	v_mfma_f32_32x32x16_bf16 v[80:95], v[198:201], v[146:149], v[16:31]
	v_exp_f32_e32 v96, v96
	v_exp_f32_e32 v97, v97
	v_exp_f32_e32 v98, v98
	v_add_f32_e32 v145, v145, v96
	v_exp_f32_e32 v99, v99
	v_mfma_f32_32x32x16_bf16 v[80:95], v[202:205], v[150:153], v[80:95]
	v_add_f32_e32 v145, v145, v97
	v_cvt_pk_bf16_f32 v120, v96, v97
	v_exp_f32_e32 v100, v100
	v_add_f32_e32 v145, v145, v98
	v_exp_f32_e32 v101, v101
	v_mfma_f32_32x32x16_bf16 v[80:95], v[206:209], v[154:157], v[80:95]
	v_add_f32_e32 v145, v145, v99
	v_cvt_pk_bf16_f32 v121, v98, v99
	v_exp_f32_e32 v102, v102
	v_add_f32_e32 v145, v145, v100
	v_exp_f32_e32 v103, v103
	v_add_f32_e32 v145, v145, v101
	v_mfma_f32_32x32x16_bf16 v[80:95], v[128:131], v[158:161], v[80:95]
	v_cvt_pk_bf16_f32 v122, v100, v101
	v_exp_f32_e32 v104, v104
	v_add_f32_e32 v145, v145, v102
	v_exp_f32_e32 v105, v105
	v_add_f32_e32 v145, v145, v103
	v_cvt_pk_bf16_f32 v123, v102, v103
	s_waitcnt lgkmcnt(6)
	v_mfma_f32_32x32x16_bf16 v[64:79], v[162:165], v[112:115], v[64:79]
	v_exp_f32_e32 v106, v106
	v_add_f32_e32 v145, v145, v104
	v_exp_f32_e32 v107, v107
	v_add_f32_e32 v145, v145, v105
	v_cvt_pk_bf16_f32 v124, v104, v105
	v_exp_f32_e32 v108, v108
	s_waitcnt lgkmcnt(4)
	v_mfma_f32_32x32x16_bf16 v[48:63], v[166:169], v[112:115], v[48:63]
	v_add_f32_e32 v145, v145, v106
	v_exp_f32_e32 v109, v109
	v_add_f32_e32 v145, v145, v107
	v_cvt_pk_bf16_f32 v125, v106, v107
	v_exp_f32_e32 v110, v110
	s_waitcnt lgkmcnt(2)
	v_mfma_f32_32x32x16_bf16 v[64:79], v[214:217], v[116:119], v[64:79]
	v_add_f32_e32 v145, v145, v108
	v_exp_f32_e32 v111, v111
	v_add_f32_e32 v145, v145, v109
	v_cvt_pk_bf16_f32 v126, v108, v109
	v_add_f32_e32 v145, v145, v110
	v_add_f32_e32 v145, v145, v111
	v_cvt_pk_bf16_f32 v127, v110, v111
	s_waitcnt lgkmcnt(0)
; __device__ __forceinline__ void attn_pass_A2(const int tid, unsigned char* smem, const bf16_t* Q0w, int qpitch, const bf16_t* Kb, int kpitch, const bf16_t* Vb, int vpitch,
;                                              int b, int ntiles, float kmax, f32x16 (&o)[2][2], float (&linv)[2]) {
;     ...
;     for (int kt = 0; kt < ntiles; ++kt) {
;         if (kt + 1 < ntiles) gload(kt + 1);
;         const unsigned char* Ks = smem + (kt & 1) * BUF; const unsigned char* Vs = Ks + KBYTES;
;         const unsigned char* kp = Ks + r32 * KP + hi * 16;
;         const unsigned char* vp = Vs + (4 * hi + q4) * VP + (16 * nhalf + 4 * p4) * 2;
; #pragma unroll
;         for (int kb = 0; kb < 2; ++kb) {
;             bf16x8 pf[2][2];
;             {
;                 f32x16 s0, s1;
; #pragma unroll
;                 for (int r = 0; r < 16; ++r) { s0[r] = nshift[0]; s1[r] = nshift[1]; }
; #pragma unroll
;                 for (int ds = 0; ds < 4; ++ds) {
;                     const bf16x8 kf = *(const bf16x8*)(kp + kb * 32 * KP + ds * 32);
;                     const bf16x8 q0 = *(const bf16x8*)(qs + ds * 32), q1 = *(const bf16x8*)(qs + 32 * KP + ds * 32);
;                     s0 = __builtin_amdgcn_mfma_f32_32x32x16_bf16(kf, q0, s0, 0, 0, 0);
;                     s1 = __builtin_amdgcn_mfma_f32_32x32x16_bf16(kf, q1, s1, 0, 0, 0);
;                 }
;                 float l0 = 0.f, l1 = 0.f;
; #pragma unroll
;                 for (int r = 0; r < 16; ++r) { s0[r] = __builtin_amdgcn_exp2f(s0[r]); l0 += s0[r]; }
; #pragma unroll
;                 for (int r = 0; r < 16; ++r) { s1[r] = __builtin_amdgcn_exp2f(s1[r]); l1 += s1[r]; }
;                 lsum[0] += l0; lsum[1] += l1;
; #pragma unroll
;                 for (int j = 0; j < 2; ++j) {
;                     u32x4 w0, w1;
;                     w0.x = cvt_pk_bf16(s0[8 * j + 0], s0[8 * j + 1]); w0.y = cvt_pk_bf16(s0[8 * j + 2], s0[8 * j + 3]); w0.z = cvt_pk_bf16(s0[8 * j + 4], s0[8 * j + 5]); w0.w = cvt_pk_bf16(s0[8 * j + 6], s0[8 * j + 7]);
;                     w1.x = cvt_pk_bf16(s1[8 * j + 0], s1[8 * j + 1]); w1.y = cvt_pk_bf16(s1[8 * j + 2], s1[8 * j + 3]); w1.z = cvt_pk_bf16(s1[8 * j + 4], s1[8 * j + 5]); w1.w = cvt_pk_bf16(s1[8 * j + 6], s1[8 * j + 7]);
;                     pf[0][j] = __builtin_bit_cast(bf16x8, w0); pf[1][j] = __builtin_bit_cast(bf16x8, w1);
;                 }
;             }
	v_mfma_f32_32x32x16_bf16 v[48:63], v[218:221], v[116:119], v[48:63]
	v_mfma_f32_32x32x16_bf16 v[96:111], v[198:201], v[176:179], v[16:31]
	ds_read_b128 v[198:201], v170 offset:32768
	v_exp_f32_e32 v80, v80
	v_exp_f32_e32 v81, v81
	v_exp_f32_e32 v82, v82
	v_add_f32_e32 v144, v144, v80
	v_exp_f32_e32 v83, v83
	v_mfma_f32_32x32x16_bf16 v[96:111], v[202:205], v[180:183], v[96:111]
	ds_read_b128 v[202:205], v171 offset:32768
	v_add_f32_e32 v144, v144, v81
	v_cvt_pk_bf16_f32 v112, v80, v81
	v_exp_f32_e32 v84, v84
	v_add_f32_e32 v144, v144, v82
	v_exp_f32_e32 v85, v85
	v_mfma_f32_32x32x16_bf16 v[96:111], v[206:209], v[184:187], v[96:111]
	ds_read_b128 v[206:209], v210 offset:32768
	v_add_f32_e32 v144, v144, v83
	v_cvt_pk_bf16_f32 v113, v82, v83
	v_exp_f32_e32 v86, v86
	v_add_f32_e32 v144, v144, v84
	v_exp_f32_e32 v87, v87
	v_add_f32_e32 v144, v144, v85
	v_mfma_f32_32x32x16_bf16 v[96:111], v[128:131], v[188:191], v[96:111]
	ds_read_b128 v[128:131], v222 offset:32768
	v_cvt_pk_bf16_f32 v114, v84, v85
	v_exp_f32_e32 v88, v88
	v_add_f32_e32 v144, v144, v86
	v_exp_f32_e32 v89, v89
	v_add_f32_e32 v144, v144, v87
	v_cvt_pk_bf16_f32 v115, v86, v87
	v_mfma_f32_32x32x16_bf16 v[32:47], v[162:165], v[120:123], v[32:47]
	ds_read_b64_tr_b16 v[162:163], v223 offset:28672
	ds_read_b64_tr_b16 v[164:165], v223 offset:29696
	v_exp_f32_e32 v90, v90
	v_add_f32_e32 v144, v144, v88
	v_exp_f32_e32 v91, v91
	v_add_f32_e32 v144, v144, v89
	v_cvt_pk_bf16_f32 v116, v88, v89
	v_exp_f32_e32 v92, v92
	v_mfma_f32_32x32x16_bf16 v[0:15], v[166:169], v[120:123], v[0:15]
	ds_read_b64_tr_b16 v[166:167], v224 offset:28672
	ds_read_b64_tr_b16 v[168:169], v224 offset:29696
	v_add_f32_e32 v144, v144, v90
	v_exp_f32_e32 v93, v93
	v_add_f32_e32 v144, v144, v91
	v_cvt_pk_bf16_f32 v117, v90, v91
	v_exp_f32_e32 v94, v94
	v_mfma_f32_32x32x16_bf16 v[32:47], v[214:217], v[124:127], v[32:47]
	ds_read_b64_tr_b16 v[214:215], v223 offset:30720
	ds_read_b64_tr_b16 v[216:217], v223 offset:31744
	v_add_f32_e32 v144, v144, v92
	v_exp_f32_e32 v95, v95
	v_add_f32_e32 v144, v144, v93
	v_cvt_pk_bf16_f32 v118, v92, v93
	v_add_f32_e32 v144, v144, v94
	v_add_f32_e32 v144, v144, v95
	v_cvt_pk_bf16_f32 v119, v94, v95
	v_mfma_f32_32x32x16_bf16 v[0:15], v[218:221], v[124:127], v[0:15]
	ds_read_b64_tr_b16 v[218:219], v224 offset:30720
	ds_read_b64_tr_b16 v[220:221], v224 offset:31744
	s_waitcnt lgkmcnt(11)
	v_mfma_f32_32x32x16_bf16 v[80:95], v[198:201], v[146:149], v[16:31]
	v_exp_f32_e32 v96, v96
	v_exp_f32_e32 v97, v97
	v_exp_f32_e32 v98, v98
	v_add_f32_e32 v145, v145, v96
	v_exp_f32_e32 v99, v99
	s_waitcnt lgkmcnt(10)
	v_mfma_f32_32x32x16_bf16 v[80:95], v[202:205], v[150:153], v[80:95]
	v_add_f32_e32 v145, v145, v97
	v_cvt_pk_bf16_f32 v120, v96, v97
	v_exp_f32_e32 v100, v100
	v_add_f32_e32 v145, v145, v98
	v_exp_f32_e32 v101, v101
	s_waitcnt lgkmcnt(9)
	v_mfma_f32_32x32x16_bf16 v[80:95], v[206:209], v[154:157], v[80:95]
	v_add_f32_e32 v145, v145, v99
	v_cvt_pk_bf16_f32 v121, v98, v99
	v_exp_f32_e32 v102, v102
	v_add_f32_e32 v145, v145, v100
	v_exp_f32_e32 v103, v103
	v_add_f32_e32 v145, v145, v101
	s_waitcnt lgkmcnt(8)
	v_mfma_f32_32x32x16_bf16 v[80:95], v[128:131], v[158:161], v[80:95]
	v_cvt_pk_bf16_f32 v122, v100, v101
	v_exp_f32_e32 v104, v104
	v_add_f32_e32 v145, v145, v102
	v_exp_f32_e32 v105, v105
	v_add_f32_e32 v145, v145, v103
	v_cvt_pk_bf16_f32 v123, v102, v103
	s_waitcnt lgkmcnt(6)
	v_mfma_f32_32x32x16_bf16 v[64:79], v[162:165], v[112:115], v[64:79]
	v_exp_f32_e32 v106, v106
	v_add_f32_e32 v145, v145, v104
	v_exp_f32_e32 v107, v107
	v_add_f32_e32 v145, v145, v105
	v_cvt_pk_bf16_f32 v124, v104, v105
	v_exp_f32_e32 v108, v108
	s_waitcnt lgkmcnt(4)
	v_mfma_f32_32x32x16_bf16 v[48:63], v[166:169], v[112:115], v[48:63]
	v_add_f32_e32 v145, v145, v106
	v_exp_f32_e32 v109, v109
	v_add_f32_e32 v145, v145, v107
	v_cvt_pk_bf16_f32 v125, v106, v107
	v_exp_f32_e32 v110, v110
	s_waitcnt lgkmcnt(2)
	v_mfma_f32_32x32x16_bf16 v[64:79], v[214:217], v[116:119], v[64:79]
	v_add_f32_e32 v145, v145, v108
	v_exp_f32_e32 v111, v111
	v_add_f32_e32 v145, v145, v109
	v_cvt_pk_bf16_f32 v126, v108, v109
	v_add_f32_e32 v145, v145, v110
	v_add_f32_e32 v145, v145, v111
	v_cvt_pk_bf16_f32 v127, v110, v111
	s_waitcnt lgkmcnt(0)
	v_mfma_f32_32x32x16_bf16 v[48:63], v[218:221], v[116:119], v[48:63]
	v_mfma_f32_32x32x16_bf16 v[96:111], v[198:201], v[176:179], v[16:31]
	ds_read_b128 v[198:201], v170 offset:36864
	v_exp_f32_e32 v80, v80
	v_exp_f32_e32 v81, v81
	v_exp_f32_e32 v82, v82
	v_add_f32_e32 v144, v144, v80
	v_exp_f32_e32 v83, v83
	v_mfma_f32_32x32x16_bf16 v[96:111], v[202:205], v[180:183], v[96:111]
	ds_read_b128 v[202:205], v171 offset:36864
	v_add_f32_e32 v144, v144, v81
	v_cvt_pk_bf16_f32 v112, v80, v81
	v_exp_f32_e32 v84, v84
	v_add_f32_e32 v144, v144, v82
	v_exp_f32_e32 v85, v85
	v_mfma_f32_32x32x16_bf16 v[96:111], v[206:209], v[184:187], v[96:111]
	ds_read_b128 v[206:209], v210 offset:36864
	v_add_f32_e32 v144, v144, v83
	v_cvt_pk_bf16_f32 v113, v82, v83
	v_exp_f32_e32 v86, v86
	v_add_f32_e32 v144, v144, v84
	v_exp_f32_e32 v87, v87
	v_add_f32_e32 v144, v144, v85
	v_mfma_f32_32x32x16_bf16 v[96:111], v[128:131], v[188:191], v[96:111]
	ds_read_b128 v[128:131], v222 offset:36864
	v_cvt_pk_bf16_f32 v114, v84, v85
	v_exp_f32_e32 v88, v88
	v_add_f32_e32 v144, v144, v86
	v_exp_f32_e32 v89, v89
	v_add_f32_e32 v144, v144, v87
	v_cvt_pk_bf16_f32 v115, v86, v87
	v_mfma_f32_32x32x16_bf16 v[32:47], v[162:165], v[120:123], v[32:47]
	ds_read_b64_tr_b16 v[162:163], v223 offset:40960
	ds_read_b64_tr_b16 v[164:165], v223 offset:41984
	v_exp_f32_e32 v90, v90
	v_add_f32_e32 v144, v144, v88
	v_exp_f32_e32 v91, v91
	v_add_f32_e32 v144, v144, v89
	v_cvt_pk_bf16_f32 v116, v88, v89
	v_exp_f32_e32 v92, v92
	v_mfma_f32_32x32x16_bf16 v[0:15], v[166:169], v[120:123], v[0:15]
	ds_read_b64_tr_b16 v[166:167], v224 offset:40960
	ds_read_b64_tr_b16 v[168:169], v224 offset:41984
	s_add_i32 s59, s59, 1
	v_add_f32_e32 v144, v144, v90
	v_exp_f32_e32 v93, v93
	v_add_f32_e32 v144, v144, v91
	v_cvt_pk_bf16_f32 v117, v90, v91
	v_exp_f32_e32 v94, v94
	v_mfma_f32_32x32x16_bf16 v[32:47], v[214:217], v[124:127], v[32:47]
	ds_read_b64_tr_b16 v[214:215], v223 offset:43008
	ds_read_b64_tr_b16 v[216:217], v223 offset:44032
	v_add_f32_e32 v144, v144, v92
	v_exp_f32_e32 v95, v95
	v_add_f32_e32 v144, v144, v93
	v_cvt_pk_bf16_f32 v118, v92, v93
	v_add_f32_e32 v144, v144, v94
	v_add_f32_e32 v144, v144, v95
	v_cvt_pk_bf16_f32 v119, v94, v95
	v_mfma_f32_32x32x16_bf16 v[0:15], v[218:221], v[124:127], v[0:15]
	ds_read_b64_tr_b16 v[218:219], v224 offset:43008
	ds_read_b64_tr_b16 v[220:221], v224 offset:44032
	s_waitcnt vmcnt(0) lgkmcnt(8)
	s_barrier
; __device__ __forceinline__ void attn_pass_A2(const int tid, unsigned char* smem, const bf16_t* Q0w, int qpitch, const bf16_t* Kb, int kpitch, const bf16_t* Vb, int vpitch,
;                                              int b, int ntiles, float kmax, f32x16 (&o)[2][2], float (&linv)[2]) {
;     ...
;     for (int kt = 0; kt < ntiles; ++kt) {
;         if (kt + 1 < ntiles) gload(kt + 1);
;         const unsigned char* Ks = smem + (kt & 1) * BUF; const unsigned char* Vs = Ks + KBYTES;
;         const unsigned char* kp = Ks + r32 * KP + hi * 16;
;         const unsigned char* vp = Vs + (4 * hi + q4) * VP + (16 * nhalf + 4 * p4) * 2;
; #pragma unroll
;         for (int kb = 0; kb < 2; ++kb) {
;             bf16x8 pf[2][2];
;             {
;                 f32x16 s0, s1;
; #pragma unroll
;                 for (int r = 0; r < 16; ++r) { s0[r] = nshift[0]; s1[r] = nshift[1]; }
; #pragma unroll
;                 for (int ds = 0; ds < 4; ++ds) {
;                     const bf16x8 kf = *(const bf16x8*)(kp + kb * 32 * KP + ds * 32);
;                     const bf16x8 q0 = *(const bf16x8*)(qs + ds * 32), q1 = *(const bf16x8*)(qs + 32 * KP + ds * 32);
;                     s0 = __builtin_amdgcn_mfma_f32_32x32x16_bf16(kf, q0, s0, 0, 0, 0);
;                     s1 = __builtin_amdgcn_mfma_f32_32x32x16_bf16(kf, q1, s1, 0, 0, 0);
;                 }
;                 float l0 = 0.f, l1 = 0.f;
; #pragma unroll
;                 for (int r = 0; r < 16; ++r) { s0[r] = __builtin_amdgcn_exp2f(s0[r]); l0 += s0[r]; }
; #pragma unroll
;                 for (int r = 0; r < 16; ++r) { s1[r] = __builtin_amdgcn_exp2f(s1[r]); l1 += s1[r]; }
;                 lsum[0] += l0; lsum[1] += l1;
; #pragma unroll
;                 for (int j = 0; j < 2; ++j) {
;                     u32x4 w0, w1;
;                     w0.x = cvt_pk_bf16(s0[8 * j + 0], s0[8 * j + 1]); w0.y = cvt_pk_bf16(s0[8 * j + 2], s0[8 * j + 3]); w0.z = cvt_pk_bf16(s0[8 * j + 4], s0[8 * j + 5]); w0.w = cvt_pk_bf16(s0[8 * j + 6], s0[8 * j + 7]);
;                     w1.x = cvt_pk_bf16(s1[8 * j + 0], s1[8 * j + 1]); w1.y = cvt_pk_bf16(s1[8 * j + 2], s1[8 * j + 3]); w1.z = cvt_pk_bf16(s1[8 * j + 4], s1[8 * j + 5]); w1.w = cvt_pk_bf16(s1[8 * j + 6], s1[8 * j + 7]);
;                     pf[0][j] = __builtin_bit_cast(bf16x8, w0); pf[1][j] = __builtin_bit_cast(bf16x8, w1);
;                 }
;             }
	v_mfma_f32_32x32x16_bf16 v[80:95], v[198:201], v[146:149], v[16:31]
	v_exp_f32_e32 v96, v96
	v_exp_f32_e32 v97, v97
	v_exp_f32_e32 v98, v98
	v_add_f32_e32 v145, v145, v96
	v_exp_f32_e32 v99, v99
	v_mfma_f32_32x32x16_bf16 v[80:95], v[202:205], v[150:153], v[80:95]
	v_add_f32_e32 v145, v145, v97
	v_cvt_pk_bf16_f32 v120, v96, v97
	v_exp_f32_e32 v100, v100
	v_add_f32_e32 v145, v145, v98
	v_exp_f32_e32 v101, v101
	v_mfma_f32_32x32x16_bf16 v[80:95], v[206:209], v[154:157], v[80:95]
	v_add_f32_e32 v145, v145, v99
	v_cvt_pk_bf16_f32 v121, v98, v99
	v_exp_f32_e32 v102, v102
	v_add_f32_e32 v145, v145, v100
	v_exp_f32_e32 v103, v103
	v_add_f32_e32 v145, v145, v101
	v_mfma_f32_32x32x16_bf16 v[80:95], v[128:131], v[158:161], v[80:95]
	v_cvt_pk_bf16_f32 v122, v100, v101
	v_exp_f32_e32 v104, v104
	v_add_f32_e32 v145, v145, v102
	v_exp_f32_e32 v105, v105
	v_add_f32_e32 v145, v145, v103
	v_cvt_pk_bf16_f32 v123, v102, v103
	s_waitcnt lgkmcnt(6)
	v_mfma_f32_32x32x16_bf16 v[64:79], v[162:165], v[112:115], v[64:79]
	v_exp_f32_e32 v106, v106
	v_add_f32_e32 v145, v145, v104
	v_exp_f32_e32 v107, v107
	v_add_f32_e32 v145, v145, v105
	v_cvt_pk_bf16_f32 v124, v104, v105
	v_exp_f32_e32 v108, v108
	s_waitcnt lgkmcnt(4)
	v_mfma_f32_32x32x16_bf16 v[48:63], v[166:169], v[112:115], v[48:63]
	v_add_f32_e32 v145, v145, v106
	v_exp_f32_e32 v109, v109
	v_add_f32_e32 v145, v145, v107
	v_cvt_pk_bf16_f32 v125, v106, v107
	v_exp_f32_e32 v110, v110
	s_waitcnt lgkmcnt(2)
	v_mfma_f32_32x32x16_bf16 v[64:79], v[214:217], v[116:119], v[64:79]
	v_add_f32_e32 v145, v145, v108
	v_exp_f32_e32 v111, v111
	v_add_f32_e32 v145, v145, v109
	v_cvt_pk_bf16_f32 v126, v108, v109
	v_add_f32_e32 v145, v145, v110
	v_add_f32_e32 v145, v145, v111
	v_cvt_pk_bf16_f32 v127, v110, v111
	s_waitcnt lgkmcnt(0)
	v_mfma_f32_32x32x16_bf16 v[48:63], v[218:221], v[116:119], v[48:63]
	v_mfma_f32_32x32x16_bf16 v[96:111], v[198:201], v[176:179], v[16:31]
	ds_read_b128 v[198:201], v170 offset:49152
	v_exp_f32_e32 v80, v80
	v_exp_f32_e32 v81, v81
	v_exp_f32_e32 v82, v82
	v_add_f32_e32 v144, v144, v80
	v_exp_f32_e32 v83, v83
	v_mfma_f32_32x32x16_bf16 v[96:111], v[202:205], v[180:183], v[96:111]
	ds_read_b128 v[202:205], v171 offset:49152
	v_add_f32_e32 v144, v144, v81
	v_cvt_pk_bf16_f32 v112, v80, v81
	v_exp_f32_e32 v84, v84
	v_add_f32_e32 v144, v144, v82
	v_exp_f32_e32 v85, v85
	v_mfma_f32_32x32x16_bf16 v[96:111], v[206:209], v[184:187], v[96:111]
	ds_read_b128 v[206:209], v210 offset:49152
	v_add_f32_e32 v144, v144, v83
	v_cvt_pk_bf16_f32 v113, v82, v83
	v_exp_f32_e32 v86, v86
	v_add_f32_e32 v144, v144, v84
	v_exp_f32_e32 v87, v87
	v_add_f32_e32 v144, v144, v85
	v_mfma_f32_32x32x16_bf16 v[96:111], v[128:131], v[188:191], v[96:111]
	ds_read_b128 v[128:131], v222 offset:49152
	v_cvt_pk_bf16_f32 v114, v84, v85
	v_exp_f32_e32 v88, v88
	v_add_f32_e32 v144, v144, v86
	v_exp_f32_e32 v89, v89
	v_add_f32_e32 v144, v144, v87
	v_cvt_pk_bf16_f32 v115, v86, v87
	v_mfma_f32_32x32x16_bf16 v[32:47], v[162:165], v[120:123], v[32:47]
	ds_read_b64_tr_b16 v[162:163], v223 offset:45056
	ds_read_b64_tr_b16 v[164:165], v223 offset:46080
	v_exp_f32_e32 v90, v90
	v_add_f32_e32 v144, v144, v88
	v_exp_f32_e32 v91, v91
	v_add_f32_e32 v144, v144, v89
	v_cvt_pk_bf16_f32 v116, v88, v89
	v_exp_f32_e32 v92, v92
	v_mfma_f32_32x32x16_bf16 v[0:15], v[166:169], v[120:123], v[0:15]
	ds_read_b64_tr_b16 v[166:167], v224 offset:45056
	ds_read_b64_tr_b16 v[168:169], v224 offset:46080
	v_add_f32_e32 v144, v144, v90
	v_exp_f32_e32 v93, v93
	v_add_f32_e32 v144, v144, v91
	v_cvt_pk_bf16_f32 v117, v90, v91
	v_exp_f32_e32 v94, v94
	v_mfma_f32_32x32x16_bf16 v[32:47], v[214:217], v[124:127], v[32:47]
	ds_read_b64_tr_b16 v[214:215], v223 offset:47104
	ds_read_b64_tr_b16 v[216:217], v223 offset:48128
	v_add_f32_e32 v144, v144, v92
	v_exp_f32_e32 v95, v95
	v_add_f32_e32 v144, v144, v93
	v_cvt_pk_bf16_f32 v118, v92, v93
	v_add_f32_e32 v144, v144, v94
	v_add_f32_e32 v144, v144, v95
	v_cvt_pk_bf16_f32 v119, v94, v95
	v_mfma_f32_32x32x16_bf16 v[0:15], v[218:221], v[124:127], v[0:15]
	ds_read_b64_tr_b16 v[218:219], v224 offset:47104
	ds_read_b64_tr_b16 v[220:221], v224 offset:48128
	s_waitcnt lgkmcnt(11)
	v_mfma_f32_32x32x16_bf16 v[80:95], v[198:201], v[146:149], v[16:31]
	v_exp_f32_e32 v96, v96
	v_exp_f32_e32 v97, v97
	v_exp_f32_e32 v98, v98
	v_add_f32_e32 v145, v145, v96
	v_exp_f32_e32 v99, v99
	s_waitcnt lgkmcnt(10)
	v_mfma_f32_32x32x16_bf16 v[80:95], v[202:205], v[150:153], v[80:95]
	v_add_f32_e32 v145, v145, v97
	v_cvt_pk_bf16_f32 v120, v96, v97
	v_exp_f32_e32 v100, v100
	v_add_f32_e32 v145, v145, v98
	v_exp_f32_e32 v101, v101
	s_waitcnt lgkmcnt(9)
	v_mfma_f32_32x32x16_bf16 v[80:95], v[206:209], v[154:157], v[80:95]
	v_add_f32_e32 v145, v145, v99
	v_cvt_pk_bf16_f32 v121, v98, v99
	v_exp_f32_e32 v102, v102
	v_add_f32_e32 v145, v145, v100
	v_exp_f32_e32 v103, v103
	v_add_f32_e32 v145, v145, v101
	s_waitcnt lgkmcnt(8)
	v_mfma_f32_32x32x16_bf16 v[80:95], v[128:131], v[158:161], v[80:95]
	v_cvt_pk_bf16_f32 v122, v100, v101
	v_exp_f32_e32 v104, v104
	v_add_f32_e32 v145, v145, v102
	v_exp_f32_e32 v105, v105
	v_add_f32_e32 v145, v145, v103
	v_cvt_pk_bf16_f32 v123, v102, v103
	s_waitcnt lgkmcnt(6)
	v_mfma_f32_32x32x16_bf16 v[64:79], v[162:165], v[112:115], v[64:79]
	v_exp_f32_e32 v106, v106
	v_add_f32_e32 v145, v145, v104
	v_exp_f32_e32 v107, v107
	v_add_f32_e32 v145, v145, v105
	v_cvt_pk_bf16_f32 v124, v104, v105
	v_exp_f32_e32 v108, v108
	s_waitcnt lgkmcnt(4)
	v_mfma_f32_32x32x16_bf16 v[48:63], v[166:169], v[112:115], v[48:63]
	v_add_f32_e32 v145, v145, v106
	v_exp_f32_e32 v109, v109
	v_add_f32_e32 v145, v145, v107
	v_cvt_pk_bf16_f32 v125, v106, v107
	v_exp_f32_e32 v110, v110
	s_waitcnt lgkmcnt(2)
; __device__ __forceinline__ void attn_pass_A2(const int tid, unsigned char* smem, const bf16_t* Q0w, int qpitch, const bf16_t* Kb, int kpitch, const bf16_t* Vb, int vpitch,
;                                              int b, int ntiles, float kmax, f32x16 (&o)[2][2], float (&linv)[2]) {
;     ...
;     for (int kt = 0; kt < ntiles; ++kt) {
;         if (kt + 1 < ntiles) gload(kt + 1);
;         const unsigned char* Ks = smem + (kt & 1) * BUF; const unsigned char* Vs = Ks + KBYTES;
;         const unsigned char* kp = Ks + r32 * KP + hi * 16;
;         const unsigned char* vp = Vs + (4 * hi + q4) * VP + (16 * nhalf + 4 * p4) * 2;
; #pragma unroll
;         for (int kb = 0; kb < 2; ++kb) {
;             bf16x8 pf[2][2];
;             {
;                 f32x16 s0, s1;
; #pragma unroll
;                 for (int r = 0; r < 16; ++r) { s0[r] = nshift[0]; s1[r] = nshift[1]; }
; #pragma unroll
;                 for (int ds = 0; ds < 4; ++ds) {
;                     const bf16x8 kf = *(const bf16x8*)(kp + kb * 32 * KP + ds * 32);
;                     const bf16x8 q0 = *(const bf16x8*)(qs + ds * 32), q1 = *(const bf16x8*)(qs + 32 * KP + ds * 32);
;                     s0 = __builtin_amdgcn_mfma_f32_32x32x16_bf16(kf, q0, s0, 0, 0, 0);
;                     s1 = __builtin_amdgcn_mfma_f32_32x32x16_bf16(kf, q1, s1, 0, 0, 0);
;                 }
;                 float l0 = 0.f, l1 = 0.f;
; #pragma unroll
;                 for (int r = 0; r < 16; ++r) { s0[r] = __builtin_amdgcn_exp2f(s0[r]); l0 += s0[r]; }
; #pragma unroll
;                 for (int r = 0; r < 16; ++r) { s1[r] = __builtin_amdgcn_exp2f(s1[r]); l1 += s1[r]; }
;                 lsum[0] += l0; lsum[1] += l1;
; #pragma unroll
;                 for (int j = 0; j < 2; ++j) {
;                     u32x4 w0, w1;
;                     w0.x = cvt_pk_bf16(s0[8 * j + 0], s0[8 * j + 1]); w0.y = cvt_pk_bf16(s0[8 * j + 2], s0[8 * j + 3]); w0.z = cvt_pk_bf16(s0[8 * j + 4], s0[8 * j + 5]); w0.w = cvt_pk_bf16(s0[8 * j + 6], s0[8 * j + 7]);
;                     w1.x = cvt_pk_bf16(s1[8 * j + 0], s1[8 * j + 1]); w1.y = cvt_pk_bf16(s1[8 * j + 2], s1[8 * j + 3]); w1.z = cvt_pk_bf16(s1[8 * j + 4], s1[8 * j + 5]); w1.w = cvt_pk_bf16(s1[8 * j + 6], s1[8 * j + 7]);
;                     pf[0][j] = __builtin_bit_cast(bf16x8, w0); pf[1][j] = __builtin_bit_cast(bf16x8, w1);
;                 }
;             }
	v_mfma_f32_32x32x16_bf16 v[64:79], v[214:217], v[116:119], v[64:79]
	v_add_f32_e32 v145, v145, v108
	v_exp_f32_e32 v111, v111
	v_add_f32_e32 v145, v145, v109
	v_cvt_pk_bf16_f32 v126, v108, v109
	v_add_f32_e32 v145, v145, v110
	v_add_f32_e32 v145, v145, v111
	v_cvt_pk_bf16_f32 v127, v110, v111
	s_waitcnt lgkmcnt(0)
	v_mfma_f32_32x32x16_bf16 v[48:63], v[218:221], v[116:119], v[48:63]
	v_mfma_f32_32x32x16_bf16 v[96:111], v[198:201], v[176:179], v[16:31]
	ds_read_b128 v[198:201], v170 offset:53248
	v_exp_f32_e32 v80, v80
	v_exp_f32_e32 v81, v81
	v_exp_f32_e32 v82, v82
	v_add_f32_e32 v144, v144, v80
	v_exp_f32_e32 v83, v83
	v_mfma_f32_32x32x16_bf16 v[96:111], v[202:205], v[180:183], v[96:111]
	ds_read_b128 v[202:205], v171 offset:53248
	v_add_f32_e32 v144, v144, v81
	v_cvt_pk_bf16_f32 v112, v80, v81
	v_exp_f32_e32 v84, v84
	v_add_f32_e32 v144, v144, v82
	v_exp_f32_e32 v85, v85
	v_mfma_f32_32x32x16_bf16 v[96:111], v[206:209], v[184:187], v[96:111]
	ds_read_b128 v[206:209], v210 offset:53248
	v_add_f32_e32 v144, v144, v83
	v_cvt_pk_bf16_f32 v113, v82, v83
	v_exp_f32_e32 v86, v86
	v_add_f32_e32 v144, v144, v84
	v_exp_f32_e32 v87, v87
	v_add_f32_e32 v144, v144, v85
	v_mfma_f32_32x32x16_bf16 v[96:111], v[128:131], v[188:191], v[96:111]
	ds_read_b128 v[128:131], v222 offset:53248
	v_cvt_pk_bf16_f32 v114, v84, v85
	v_exp_f32_e32 v88, v88
	v_add_f32_e32 v144, v144, v86
	v_exp_f32_e32 v89, v89
	v_add_f32_e32 v144, v144, v87
	v_cvt_pk_bf16_f32 v115, v86, v87
	v_mfma_f32_32x32x16_bf16 v[32:47], v[162:165], v[120:123], v[32:47]
	ds_read_b64_tr_b16 v[162:163], v223 offset:57344
	ds_read_b64_tr_b16 v[164:165], v223 offset:58368
	v_exp_f32_e32 v90, v90
	v_add_f32_e32 v144, v144, v88
	v_exp_f32_e32 v91, v91
	v_add_f32_e32 v144, v144, v89
	v_cvt_pk_bf16_f32 v116, v88, v89
	v_exp_f32_e32 v92, v92
	v_mfma_f32_32x32x16_bf16 v[0:15], v[166:169], v[120:123], v[0:15]
	ds_read_b64_tr_b16 v[166:167], v224 offset:57344
	ds_read_b64_tr_b16 v[168:169], v224 offset:58368
	s_add_i32 s59, s59, 1
	v_add_f32_e32 v144, v144, v90
	v_exp_f32_e32 v93, v93
	v_add_f32_e32 v144, v144, v91
	v_cvt_pk_bf16_f32 v117, v90, v91
	v_exp_f32_e32 v94, v94
	v_mfma_f32_32x32x16_bf16 v[32:47], v[214:217], v[124:127], v[32:47]
	ds_read_b64_tr_b16 v[214:215], v223 offset:59392
	ds_read_b64_tr_b16 v[216:217], v223 offset:60416
	v_add_f32_e32 v144, v144, v92
	v_exp_f32_e32 v95, v95
	v_add_f32_e32 v144, v144, v93
	v_cvt_pk_bf16_f32 v118, v92, v93
	v_add_f32_e32 v144, v144, v94
	v_add_f32_e32 v144, v144, v95
	v_cvt_pk_bf16_f32 v119, v94, v95
	v_mfma_f32_32x32x16_bf16 v[0:15], v[218:221], v[124:127], v[0:15]
	ds_read_b64_tr_b16 v[218:219], v224 offset:59392
	ds_read_b64_tr_b16 v[220:221], v224 offset:60416
	s_waitcnt lgkmcnt(8)
	s_barrier
; __device__ __forceinline__ void attn_pass_A2(const int tid, unsigned char* smem, const bf16_t* Q0w, int qpitch, const bf16_t* Kb, int kpitch, const bf16_t* Vb, int vpitch,
;                                              int b, int ntiles, float kmax, f32x16 (&o)[2][2], float (&linv)[2]) {
;     ...
;     for (int kt = 0; kt < ntiles; ++kt) {
;         if (kt + 1 < ntiles) gload(kt + 1);
;         const unsigned char* Ks = smem + (kt & 1) * BUF; const unsigned char* Vs = Ks + KBYTES;
;         const unsigned char* kp = Ks + r32 * KP + hi * 16;
;         const unsigned char* vp = Vs + (4 * hi + q4) * VP + (16 * nhalf + 4 * p4) * 2;
; #pragma unroll
;         for (int kb = 0; kb < 2; ++kb) {
;             bf16x8 pf[2][2];
;             {
;                 f32x16 s0, s1;
; #pragma unroll
;                 for (int r = 0; r < 16; ++r) { s0[r] = nshift[0]; s1[r] = nshift[1]; }
; #pragma unroll
;                 for (int ds = 0; ds < 4; ++ds) {
;                     const bf16x8 kf = *(const bf16x8*)(kp + kb * 32 * KP + ds * 32);
;                     const bf16x8 q0 = *(const bf16x8*)(qs + ds * 32), q1 = *(const bf16x8*)(qs + 32 * KP + ds * 32);
;                     s0 = __builtin_amdgcn_mfma_f32_32x32x16_bf16(kf, q0, s0, 0, 0, 0);
;                     s1 = __builtin_amdgcn_mfma_f32_32x32x16_bf16(kf, q1, s1, 0, 0, 0);
;                 }
;                 float l0 = 0.f, l1 = 0.f;
; #pragma unroll
;                 for (int r = 0; r < 16; ++r) { s0[r] = __builtin_amdgcn_exp2f(s0[r]); l0 += s0[r]; }
; #pragma unroll
;                 for (int r = 0; r < 16; ++r) { s1[r] = __builtin_amdgcn_exp2f(s1[r]); l1 += s1[r]; }
;                 lsum[0] += l0; lsum[1] += l1;
; #pragma unroll
;                 for (int j = 0; j < 2; ++j) {
;                     u32x4 w0, w1;
;                     w0.x = cvt_pk_bf16(s0[8 * j + 0], s0[8 * j + 1]); w0.y = cvt_pk_bf16(s0[8 * j + 2], s0[8 * j + 3]); w0.z = cvt_pk_bf16(s0[8 * j + 4], s0[8 * j + 5]); w0.w = cvt_pk_bf16(s0[8 * j + 6], s0[8 * j + 7]);
;                     w1.x = cvt_pk_bf16(s1[8 * j + 0], s1[8 * j + 1]); w1.y = cvt_pk_bf16(s1[8 * j + 2], s1[8 * j + 3]); w1.z = cvt_pk_bf16(s1[8 * j + 4], s1[8 * j + 5]); w1.w = cvt_pk_bf16(s1[8 * j + 6], s1[8 * j + 7]);
;                     pf[0][j] = __builtin_bit_cast(bf16x8, w0); pf[1][j] = __builtin_bit_cast(bf16x8, w1);
;                 }
;             }
	v_mfma_f32_32x32x16_bf16 v[80:95], v[198:201], v[146:149], v[16:31]
	v_exp_f32_e32 v96, v96
	v_exp_f32_e32 v97, v97
	v_exp_f32_e32 v98, v98
	v_add_f32_e32 v145, v145, v96
	v_exp_f32_e32 v99, v99
	v_mfma_f32_32x32x16_bf16 v[80:95], v[202:205], v[150:153], v[80:95]
	v_add_f32_e32 v145, v145, v97
	v_cvt_pk_bf16_f32 v120, v96, v97
	v_exp_f32_e32 v100, v100
	v_add_f32_e32 v145, v145, v98
	v_exp_f32_e32 v101, v101
	v_mfma_f32_32x32x16_bf16 v[80:95], v[206:209], v[154:157], v[80:95]
	v_add_f32_e32 v145, v145, v99
	v_cvt_pk_bf16_f32 v121, v98, v99
	v_exp_f32_e32 v102, v102
	v_add_f32_e32 v145, v145, v100
	v_exp_f32_e32 v103, v103
	v_add_f32_e32 v145, v145, v101
	v_mfma_f32_32x32x16_bf16 v[80:95], v[128:131], v[158:161], v[80:95]
	v_cvt_pk_bf16_f32 v122, v100, v101
	v_exp_f32_e32 v104, v104
	v_add_f32_e32 v145, v145, v102
	v_exp_f32_e32 v105, v105
	v_add_f32_e32 v145, v145, v103
	v_cvt_pk_bf16_f32 v123, v102, v103
	s_waitcnt lgkmcnt(6)
	v_mfma_f32_32x32x16_bf16 v[64:79], v[162:165], v[112:115], v[64:79]
	v_exp_f32_e32 v106, v106
	v_add_f32_e32 v145, v145, v104
	v_exp_f32_e32 v107, v107
	v_add_f32_e32 v145, v145, v105
	v_cvt_pk_bf16_f32 v124, v104, v105
	v_exp_f32_e32 v108, v108
	s_waitcnt lgkmcnt(4)
	v_mfma_f32_32x32x16_bf16 v[48:63], v[166:169], v[112:115], v[48:63]
	v_add_f32_e32 v145, v145, v106
	v_exp_f32_e32 v109, v109
	v_add_f32_e32 v145, v145, v107
	v_cvt_pk_bf16_f32 v125, v106, v107
	v_exp_f32_e32 v110, v110
	s_waitcnt lgkmcnt(2)
	v_mfma_f32_32x32x16_bf16 v[64:79], v[214:217], v[116:119], v[64:79]
	v_add_f32_e32 v145, v145, v108
	v_exp_f32_e32 v111, v111
	v_add_f32_e32 v145, v145, v109
	v_cvt_pk_bf16_f32 v126, v108, v109
	v_add_f32_e32 v145, v145, v110
	v_add_f32_e32 v145, v145, v111
	v_cvt_pk_bf16_f32 v127, v110, v111
	s_waitcnt lgkmcnt(0)
	v_mfma_f32_32x32x16_bf16 v[48:63], v[218:221], v[116:119], v[48:63]
	v_mfma_f32_32x32x16_bf16 v[96:111], v[198:201], v[176:179], v[16:31]
	v_exp_f32_e32 v80, v80
	v_exp_f32_e32 v81, v81
	v_exp_f32_e32 v82, v82
	v_add_f32_e32 v144, v144, v80
	v_exp_f32_e32 v83, v83
	v_mfma_f32_32x32x16_bf16 v[96:111], v[202:205], v[180:183], v[96:111]
	v_add_f32_e32 v144, v144, v81
	v_cvt_pk_bf16_f32 v112, v80, v81
	v_exp_f32_e32 v84, v84
	v_add_f32_e32 v144, v144, v82
	v_exp_f32_e32 v85, v85
	v_mfma_f32_32x32x16_bf16 v[96:111], v[206:209], v[184:187], v[96:111]
	v_add_f32_e32 v144, v144, v83
	v_cvt_pk_bf16_f32 v113, v82, v83
	v_exp_f32_e32 v86, v86
	v_add_f32_e32 v144, v144, v84
	v_exp_f32_e32 v87, v87
	v_add_f32_e32 v144, v144, v85
	v_mfma_f32_32x32x16_bf16 v[96:111], v[128:131], v[188:191], v[96:111]
	v_cvt_pk_bf16_f32 v114, v84, v85
	v_exp_f32_e32 v88, v88
	v_add_f32_e32 v144, v144, v86
	v_exp_f32_e32 v89, v89
	v_add_f32_e32 v144, v144, v87
	v_cvt_pk_bf16_f32 v115, v86, v87
	v_mfma_f32_32x32x16_bf16 v[32:47], v[162:165], v[120:123], v[32:47]
	ds_read_b64_tr_b16 v[162:163], v223 offset:61440
	ds_read_b64_tr_b16 v[164:165], v223 offset:62464
	v_exp_f32_e32 v90, v90
	v_add_f32_e32 v144, v144, v88
	v_exp_f32_e32 v91, v91
	v_add_f32_e32 v144, v144, v89
	v_cvt_pk_bf16_f32 v116, v88, v89
	v_exp_f32_e32 v92, v92
	v_mfma_f32_32x32x16_bf16 v[0:15], v[166:169], v[120:123], v[0:15]
	ds_read_b64_tr_b16 v[166:167], v224 offset:61440
	ds_read_b64_tr_b16 v[168:169], v224 offset:62464
	v_add_f32_e32 v144, v144, v90
	v_exp_f32_e32 v93, v93
	v_add_f32_e32 v144, v144, v91
	v_cvt_pk_bf16_f32 v117, v90, v91
	v_exp_f32_e32 v94, v94
	v_mfma_f32_32x32x16_bf16 v[32:47], v[214:217], v[124:127], v[32:47]
	ds_read_b64_tr_b16 v[214:215], v223 offset:63488
	ds_read_b64_tr_b16 v[216:217], v223 offset:64512
	v_add_f32_e32 v144, v144, v92
	v_exp_f32_e32 v95, v95
	v_add_f32_e32 v144, v144, v93
	v_cvt_pk_bf16_f32 v118, v92, v93
	v_add_f32_e32 v144, v144, v94
	v_add_f32_e32 v144, v144, v95
	v_cvt_pk_bf16_f32 v119, v94, v95
	v_mfma_f32_32x32x16_bf16 v[0:15], v[218:221], v[124:127], v[0:15]
	ds_read_b64_tr_b16 v[218:219], v224 offset:63488
	ds_read_b64_tr_b16 v[220:221], v224 offset:64512
	s_waitcnt lgkmcnt(6)
	v_mfma_f32_32x32x16_bf16 v[64:79], v[162:165], v[112:115], v[64:79]
	v_exp_f32_e32 v96, v96
	v_exp_f32_e32 v97, v97
	v_exp_f32_e32 v98, v98
	v_add_f32_e32 v145, v145, v96
	v_exp_f32_e32 v99, v99
	v_add_f32_e32 v145, v145, v97
	v_cvt_pk_bf16_f32 v120, v96, v97
	v_exp_f32_e32 v100, v100
	v_add_f32_e32 v145, v145, v98
	v_exp_f32_e32 v101, v101
	v_add_f32_e32 v145, v145, v99
	v_cvt_pk_bf16_f32 v121, v98, v99
	v_exp_f32_e32 v102, v102
	s_waitcnt lgkmcnt(4)
	v_mfma_f32_32x32x16_bf16 v[48:63], v[166:169], v[112:115], v[48:63]
	v_add_f32_e32 v145, v145, v100
	v_exp_f32_e32 v103, v103
	v_add_f32_e32 v145, v145, v101
	v_cvt_pk_bf16_f32 v122, v100, v101
	v_exp_f32_e32 v104, v104
	v_add_f32_e32 v145, v145, v102
	v_exp_f32_e32 v105, v105
	v_add_f32_e32 v145, v145, v103
	v_cvt_pk_bf16_f32 v123, v102, v103
	v_exp_f32_e32 v106, v106
	v_add_f32_e32 v145, v145, v104
	v_exp_f32_e32 v107, v107
	v_add_f32_e32 v145, v145, v105
	s_waitcnt lgkmcnt(2)
	v_mfma_f32_32x32x16_bf16 v[64:79], v[214:217], v[116:119], v[64:79]
	v_cvt_pk_bf16_f32 v124, v104, v105
	v_exp_f32_e32 v108, v108
	v_add_f32_e32 v145, v145, v106
	v_exp_f32_e32 v109, v109
	v_add_f32_e32 v145, v145, v107
	v_cvt_pk_bf16_f32 v125, v106, v107
	v_exp_f32_e32 v110, v110
	v_add_f32_e32 v145, v145, v108
	v_exp_f32_e32 v111, v111
	v_add_f32_e32 v145, v145, v109
	v_cvt_pk_bf16_f32 v126, v108, v109
	v_add_f32_e32 v145, v145, v110
	v_add_f32_e32 v145, v145, v111
	v_cvt_pk_bf16_f32 v127, v110, v111
	s_waitcnt lgkmcnt(0)
	v_mfma_f32_32x32x16_bf16 v[48:63], v[218:221], v[116:119], v[48:63]
	v_mfma_f32_32x32x16_bf16 v[32:47], v[162:165], v[120:123], v[32:47]
	v_mfma_f32_32x32x16_bf16 v[0:15], v[166:169], v[120:123], v[0:15]
	v_mfma_f32_32x32x16_bf16 v[32:47], v[214:217], v[124:127], v[32:47]
	v_mfma_f32_32x32x16_bf16 v[0:15], v[218:221], v[124:127], v[0:15]
	s_waitcnt lgkmcnt(0)
	s_barrier
	s_waitcnt vmcnt(0)
	s_setprio 0
